# sc1 (write-through) on the GEMM epilogue dwordx4/x2 stores so the grid barrier's L2 write-back has less dirty data
# baseline (speedup 1.0000x reference)
.LBB0_220:
	v_lshl_add_u32 v144, s48, 8, v146
	v_lshl_or_b32 v142, s83, 8, v148
	v_ashrrev_i32_e32 v145, 31, v144
	v_ashrrev_i32_e32 v143, 31, v142
	v_lshlrev_b64 v[150:151], 13, v[144:145]
	v_lshl_add_u64 v[150:151], s[70:71], 0, v[150:151]
	v_lshlrev_b64 v[152:153], 1, v[142:143]
	v_lshl_add_u64 v[142:143], v[150:151], 0, v[152:153]
	v_cvt_pk_bf16_f32 v126, v126, v127
	v_cvt_pk_bf16_f32 v127, v128, v129
	v_cvt_pk_bf16_f32 v128, v122, v123
	v_cvt_pk_bf16_f32 v129, v124, v125
	global_store_dwordx4 v[142:143], v[126:129], off sc1
	v_cvt_pk_bf16_f32 v114, v114, v115
	v_cvt_pk_bf16_f32 v115, v116, v117
	v_cvt_pk_bf16_f32 v116, v106, v107
	v_or_b32_e32 v106, 16, v144
	v_ashrrev_i32_e32 v107, 31, v106
	v_lshlrev_b64 v[106:107], 13, v[106:107]
	v_lshl_add_u64 v[106:107], s[70:71], 0, v[106:107]
	v_cvt_pk_bf16_f32 v117, v108, v109
	global_store_dwordx4 v[142:143], v[114:117], off offset:256 sc1
	s_mov_b64 s[28:29], 0x100000
	s_nop 0
	v_lshl_add_u64 v[114:115], v[106:107], 0, v[152:153]
	v_cvt_pk_bf16_f32 v106, v118, v119
	v_cvt_pk_bf16_f32 v107, v120, v121
	v_cvt_pk_bf16_f32 v108, v110, v111
	v_cvt_pk_bf16_f32 v109, v112, v113
	global_store_dwordx4 v[114:115], v[106:109], off sc1
	v_cvt_pk_bf16_f32 v98, v98, v99
	v_cvt_pk_bf16_f32 v99, v100, v101
	v_cvt_pk_bf16_f32 v100, v90, v91
	v_or_b32_e32 v90, 32, v144
	v_ashrrev_i32_e32 v91, 31, v90
	v_lshlrev_b64 v[90:91], 13, v[90:91]
	v_lshl_add_u64 v[90:91], s[70:71], 0, v[90:91]
	v_cvt_pk_bf16_f32 v101, v92, v93
	global_store_dwordx4 v[114:115], v[98:101], off offset:256 sc1
	s_nop 1
	v_lshl_add_u64 v[98:99], v[90:91], 0, v[152:153]
	v_cvt_pk_bf16_f32 v90, v102, v103
	v_cvt_pk_bf16_f32 v91, v104, v105
	v_cvt_pk_bf16_f32 v92, v94, v95
	v_cvt_pk_bf16_f32 v93, v96, v97
	global_store_dwordx4 v[98:99], v[90:93], off sc1
	v_cvt_pk_bf16_f32 v82, v82, v83
	v_cvt_pk_bf16_f32 v83, v84, v85
	v_cvt_pk_bf16_f32 v84, v74, v75
	v_or_b32_e32 v74, 48, v144
	v_ashrrev_i32_e32 v75, 31, v74
	v_lshlrev_b64 v[74:75], 13, v[74:75]
	v_lshl_add_u64 v[74:75], s[70:71], 0, v[74:75]
	v_cvt_pk_bf16_f32 v85, v76, v77
	global_store_dwordx4 v[98:99], v[82:85], off offset:256 sc1
	s_nop 1
	v_lshl_add_u64 v[82:83], v[74:75], 0, v[152:153]
	v_cvt_pk_bf16_f32 v74, v86, v87
	v_cvt_pk_bf16_f32 v75, v88, v89
	v_cvt_pk_bf16_f32 v76, v78, v79
	v_cvt_pk_bf16_f32 v77, v80, v81
	global_store_dwordx4 v[82:83], v[74:77], off sc1
	v_cvt_pk_bf16_f32 v70, v70, v71
	v_cvt_pk_bf16_f32 v71, v72, v73
	v_cvt_pk_bf16_f32 v72, v66, v67
	v_lshl_add_u64 v[66:67], v[142:143], 0, s[28:29]
	s_mov_b32 s28, 0x100000
	v_cvt_pk_bf16_f32 v73, v68, v69
	global_store_dwordx4 v[82:83], v[70:73], off offset:256 sc1
	v_cvt_pk_bf16_f32 v62, v62, v63
	v_cvt_pk_bf16_f32 v63, v64, v65
	v_cvt_pk_bf16_f32 v64, v58, v59
	v_add_co_u32_e32 v58, vcc, s28, v142
	v_cvt_pk_bf16_f32 v65, v60, v61
	s_mov_b64 s[28:29], 0x120000
	s_nop 0
	v_addc_co_u32_e32 v59, vcc, 0, v143, vcc
	global_store_dwordx4 v[58:59], v[62:65], off sc1
	v_cvt_pk_bf16_f32 v50, v50, v51
	v_cvt_pk_bf16_f32 v51, v52, v53
	v_cvt_pk_bf16_f32 v52, v42, v43
	v_cvt_pk_bf16_f32 v53, v44, v45
	global_store_dwordx4 v[66:67], v[50:53], off offset:256 sc1
	v_cvt_pk_bf16_f32 v42, v54, v55
	v_cvt_pk_bf16_f32 v43, v56, v57
	v_cvt_pk_bf16_f32 v44, v46, v47
	v_cvt_pk_bf16_f32 v45, v48, v49
	s_nop 1
	v_lshl_add_u64 v[50:51], v[142:143], 0, s[28:29]
	s_mov_b32 s28, 0x120000
	v_add_co_u32_e32 v46, vcc, s28, v142
	s_mov_b64 s[28:29], 0x140000
	s_nop 0
	v_addc_co_u32_e32 v47, vcc, 0, v143, vcc
	global_store_dwordx4 v[46:47], v[42:45], off sc1
	v_cvt_pk_bf16_f32 v34, v34, v35
	v_cvt_pk_bf16_f32 v35, v36, v37
	v_cvt_pk_bf16_f32 v36, v26, v27
	v_cvt_pk_bf16_f32 v37, v28, v29
	global_store_dwordx4 v[50:51], v[34:37], off offset:256 sc1
	v_cvt_pk_bf16_f32 v26, v38, v39
	v_cvt_pk_bf16_f32 v27, v40, v41
	v_cvt_pk_bf16_f32 v28, v30, v31
	v_cvt_pk_bf16_f32 v29, v32, v33
	s_nop 1
	v_lshl_add_u64 v[34:35], v[142:143], 0, s[28:29]
	s_mov_b32 s28, 0x140000
	v_add_co_u32_e32 v30, vcc, s28, v142
	s_mov_b64 s[28:29], 0x160000
	s_nop 0
	v_addc_co_u32_e32 v31, vcc, 0, v143, vcc
	global_store_dwordx4 v[30:31], v[26:29], off sc1
	v_cvt_pk_bf16_f32 v18, v18, v19
	v_cvt_pk_bf16_f32 v19, v20, v21
	v_cvt_pk_bf16_f32 v20, v8, v9
	v_cvt_pk_bf16_f32 v21, v10, v11
	global_store_dwordx4 v[34:35], v[18:21], off offset:256 sc1
	v_cvt_pk_bf16_f32 v8, v22, v23
	v_cvt_pk_bf16_f32 v9, v24, v25
	v_cvt_pk_bf16_f32 v10, v12, v13
	v_cvt_pk_bf16_f32 v11, v14, v15
	s_nop 1
	v_lshl_add_u64 v[18:19], v[142:143], 0, s[28:29]
	s_mov_b32 s28, 0x160000
	v_add_co_u32_e32 v12, vcc, s28, v142
	s_nop 1
	v_addc_co_u32_e32 v13, vcc, 0, v143, vcc
	global_store_dwordx4 v[12:13], v[8:11], off sc1
	v_cvt_pk_bf16_f32 v4, v4, v5
	v_cvt_pk_bf16_f32 v5, v6, v7
	v_cvt_pk_bf16_f32 v6, v0, v1
	v_cvt_pk_bf16_f32 v7, v2, v3
	global_store_dwordx4 v[18:19], v[4:7], off offset:256 sc1
	s_andn2_b64 vcc, exec, s[38:39]
	s_mov_b64 s[28:29], -1
	s_cbranch_vccnz .LBB0_212
	s_branch .LBB0_224

.LBB0_652:
	v_lshl_add_u32 v146, s44, 8, v142
	v_lshl_or_b32 v140, s86, 8, v144
	v_ashrrev_i32_e32 v147, 31, v146
	v_ashrrev_i32_e32 v141, 31, v140
	v_lshlrev_b64 v[148:149], 14, v[146:147]
	v_lshl_add_u64 v[148:149], s[70:71], 0, v[148:149]
	v_lshlrev_b64 v[150:151], 1, v[140:141]
	v_lshl_add_u64 v[140:141], v[148:149], 0, v[150:151]
	v_cvt_pk_bf16_f32 v126, v126, v127
	v_cvt_pk_bf16_f32 v127, v128, v129
	v_cvt_pk_bf16_f32 v128, v122, v123
	v_cvt_pk_bf16_f32 v129, v124, v125
	global_store_dwordx4 v[140:141], v[126:129], off sc1
	v_cvt_pk_bf16_f32 v114, v114, v115
	v_cvt_pk_bf16_f32 v115, v116, v117
	v_cvt_pk_bf16_f32 v116, v106, v107
	v_or_b32_e32 v106, 16, v146
	v_ashrrev_i32_e32 v107, 31, v106
	v_lshlrev_b64 v[106:107], 14, v[106:107]
	v_lshl_add_u64 v[106:107], s[70:71], 0, v[106:107]
	v_cvt_pk_bf16_f32 v117, v108, v109
	global_store_dwordx4 v[140:141], v[114:117], off offset:256 sc1
	s_mov_b32 s19, 0x200000
	s_mov_b64 s[28:29], 0x200000
	v_lshl_add_u64 v[114:115], v[106:107], 0, v[150:151]
	v_cvt_pk_bf16_f32 v106, v118, v119
	v_cvt_pk_bf16_f32 v107, v120, v121
	v_cvt_pk_bf16_f32 v108, v110, v111
	v_cvt_pk_bf16_f32 v109, v112, v113
	global_store_dwordx4 v[114:115], v[106:109], off sc1
	v_cvt_pk_bf16_f32 v98, v98, v99
	v_cvt_pk_bf16_f32 v99, v100, v101
	v_cvt_pk_bf16_f32 v100, v90, v91
	v_or_b32_e32 v90, 32, v146
	v_ashrrev_i32_e32 v91, 31, v90
	v_lshlrev_b64 v[90:91], 14, v[90:91]
	v_lshl_add_u64 v[90:91], s[70:71], 0, v[90:91]
	v_cvt_pk_bf16_f32 v101, v92, v93
	global_store_dwordx4 v[114:115], v[98:101], off offset:256 sc1
	s_mov_b64 s[90:91], s[62:63]
	s_nop 0
	v_lshl_add_u64 v[98:99], v[90:91], 0, v[150:151]
	v_cvt_pk_bf16_f32 v90, v102, v103
	v_cvt_pk_bf16_f32 v91, v104, v105
	v_cvt_pk_bf16_f32 v92, v94, v95
	v_cvt_pk_bf16_f32 v93, v96, v97
	global_store_dwordx4 v[98:99], v[90:93], off sc1
	v_cvt_pk_bf16_f32 v82, v82, v83
	v_cvt_pk_bf16_f32 v83, v84, v85
	v_cvt_pk_bf16_f32 v84, v74, v75
	v_or_b32_e32 v74, 48, v146
	v_ashrrev_i32_e32 v75, 31, v74
	v_lshlrev_b64 v[74:75], 14, v[74:75]
	v_lshl_add_u64 v[74:75], s[70:71], 0, v[74:75]
	v_cvt_pk_bf16_f32 v85, v76, v77
	global_store_dwordx4 v[98:99], v[82:85], off offset:256 sc1
	s_nop 1
	v_lshl_add_u64 v[82:83], v[74:75], 0, v[150:151]
	v_cvt_pk_bf16_f32 v74, v86, v87
	v_cvt_pk_bf16_f32 v75, v88, v89
	v_cvt_pk_bf16_f32 v76, v78, v79
	v_cvt_pk_bf16_f32 v77, v80, v81
	global_store_dwordx4 v[82:83], v[74:77], off sc1
	v_cvt_pk_bf16_f32 v70, v70, v71
	v_cvt_pk_bf16_f32 v71, v72, v73
	v_cvt_pk_bf16_f32 v72, v66, v67
	v_cvt_pk_bf16_f32 v73, v68, v69
	global_store_dwordx4 v[82:83], v[70:73], off offset:256 sc1
	v_cvt_pk_bf16_f32 v62, v62, v63
	v_cvt_pk_bf16_f32 v63, v64, v65
	v_cvt_pk_bf16_f32 v64, v58, v59
	v_add_co_u32_e32 v58, vcc, s19, v140
	v_lshl_add_u64 v[66:67], v[140:141], 0, s[28:29]
	s_nop 0
	v_addc_co_u32_e32 v59, vcc, 0, v141, vcc
	s_mov_b32 s19, 0x240000
	v_cvt_pk_bf16_f32 v65, v60, v61
	global_store_dwordx4 v[58:59], v[62:65], off sc1
	v_cvt_pk_bf16_f32 v50, v50, v51
	v_cvt_pk_bf16_f32 v51, v52, v53
	v_cvt_pk_bf16_f32 v52, v42, v43
	v_cvt_pk_bf16_f32 v53, v44, v45
	global_store_dwordx4 v[66:67], v[50:53], off offset:256 sc1
	s_mov_b64 s[28:29], 0x240000
	v_cvt_pk_bf16_f32 v42, v54, v55
	v_cvt_pk_bf16_f32 v43, v56, v57
	v_cvt_pk_bf16_f32 v44, v46, v47
	v_add_co_u32_e32 v46, vcc, s19, v140
	v_lshl_add_u64 v[50:51], v[140:141], 0, s[28:29]
	s_nop 0
	v_addc_co_u32_e32 v47, vcc, 0, v141, vcc
	s_mov_b32 s19, 0x280000
	v_cvt_pk_bf16_f32 v45, v48, v49
	global_store_dwordx4 v[46:47], v[42:45], off sc1
	v_cvt_pk_bf16_f32 v34, v34, v35
	v_cvt_pk_bf16_f32 v35, v36, v37
	v_cvt_pk_bf16_f32 v36, v26, v27
	v_cvt_pk_bf16_f32 v37, v28, v29
	global_store_dwordx4 v[50:51], v[34:37], off offset:256 sc1
	s_mov_b64 s[28:29], 0x280000
	v_cvt_pk_bf16_f32 v26, v38, v39
	v_cvt_pk_bf16_f32 v27, v40, v41
	v_cvt_pk_bf16_f32 v28, v30, v31
	v_add_co_u32_e32 v30, vcc, s19, v140
	v_lshl_add_u64 v[34:35], v[140:141], 0, s[28:29]
	s_nop 0
	v_addc_co_u32_e32 v31, vcc, 0, v141, vcc
	s_mov_b32 s19, 0x2c0000
	v_cvt_pk_bf16_f32 v29, v32, v33
	global_store_dwordx4 v[30:31], v[26:29], off sc1
	v_cvt_pk_bf16_f32 v18, v18, v19
	v_cvt_pk_bf16_f32 v19, v20, v21
	v_cvt_pk_bf16_f32 v20, v8, v9
	v_cvt_pk_bf16_f32 v21, v10, v11
	global_store_dwordx4 v[34:35], v[18:21], off offset:256 sc1
	v_cvt_pk_bf16_f32 v8, v22, v23
	v_cvt_pk_bf16_f32 v9, v24, v25
	v_cvt_pk_bf16_f32 v10, v12, v13
	v_add_co_u32_e32 v12, vcc, s19, v140
	s_mov_b64 s[28:29], 0x2c0000
	s_nop 0
	v_addc_co_u32_e32 v13, vcc, 0, v141, vcc
	v_lshl_add_u64 v[18:19], v[140:141], 0, s[28:29]
	s_and_b64 vcc, exec, s[38:39]
	s_mov_b64 s[28:29], -1
	v_cvt_pk_bf16_f32 v11, v14, v15
	global_store_dwordx4 v[12:13], v[8:11], off sc1
	v_cvt_pk_bf16_f32 v4, v4, v5
	v_cvt_pk_bf16_f32 v5, v6, v7
	v_cvt_pk_bf16_f32 v6, v0, v1
	v_cvt_pk_bf16_f32 v7, v2, v3
	global_store_dwordx4 v[18:19], v[4:7], off offset:256 sc1
	s_cbranch_vccnz .LBB0_643
	s_andn2_b64 vcc, exec, s[0:1]
	s_cbranch_vccnz .LBB0_642
	s_barrier
	s_branch .LBB0_642

.LBB0_720:
	v_lshl_add_u32 v162, s42, 8, v223
	v_lshl_or_b32 v136, s83, 6, v225
	v_ashrrev_i32_e32 v163, 31, v162
	v_lshlrev_b64 v[138:139], 14, v[162:163]
	v_ashrrev_i32_e32 v137, 31, v136
	v_lshl_add_u64 v[138:139], s[70:71], 0, v[138:139]
	v_lshlrev_b64 v[148:149], 1, v[136:137]
	v_lshl_add_u64 v[136:137], v[138:139], 0, v[148:149]
	v_add_co_u32_e32 v138, vcc, 0x1000, v136
	s_mov_b32 s19, 0x200000
	s_nop 0
	v_addc_co_u32_e32 v139, vcc, 0, v137, vcc
	v_add_co_u32_e32 v140, vcc, 0x2000, v136
	s_nop 1
	v_addc_co_u32_e32 v141, vcc, 0, v137, vcc
	v_add_co_u32_e32 v142, vcc, 0x3000, v136
	s_nop 1
	v_addc_co_u32_e32 v143, vcc, 0, v137, vcc
	global_load_dwordx2 v[200:201], v[136:137], off
	global_load_dwordx2 v[202:203], v[138:139], off
	global_load_dwordx2 v[196:197], v[140:141], off
	global_load_dwordx2 v[198:199], v[142:143], off
	v_add_co_u32_e32 v138, vcc, s20, v136
	s_nop 1
	v_addc_co_u32_e32 v139, vcc, 0, v137, vcc
	v_add_co_u32_e32 v140, vcc, 0x41000, v136
	s_nop 1
	v_addc_co_u32_e32 v141, vcc, 0, v137, vcc
	v_add_co_u32_e32 v142, vcc, 0x42000, v136
	s_nop 1
	v_addc_co_u32_e32 v143, vcc, 0, v137, vcc
	v_add_co_u32_e32 v144, vcc, 0x43000, v136
	s_nop 1
	v_addc_co_u32_e32 v145, vcc, 0, v137, vcc
	global_load_dwordx2 v[192:193], v[138:139], off
	global_load_dwordx2 v[194:195], v[140:141], off
	global_load_dwordx2 v[188:189], v[142:143], off
	global_load_dwordx2 v[190:191], v[144:145], off
	v_add_co_u32_e32 v138, vcc, s64, v136
	s_nop 1
	v_addc_co_u32_e32 v139, vcc, 0, v137, vcc
	v_add_co_u32_e32 v140, vcc, 0x81000, v136
	s_nop 1
	v_addc_co_u32_e32 v141, vcc, 0, v137, vcc
	v_add_co_u32_e32 v142, vcc, 0x82000, v136
	s_nop 1
	v_addc_co_u32_e32 v143, vcc, 0, v137, vcc
	v_add_co_u32_e32 v144, vcc, 0x83000, v136
	s_nop 1
	v_addc_co_u32_e32 v145, vcc, 0, v137, vcc
	global_load_dwordx2 v[184:185], v[138:139], off
	global_load_dwordx2 v[186:187], v[140:141], off
	global_load_dwordx2 v[180:181], v[142:143], off
	global_load_dwordx2 v[182:183], v[144:145], off
	v_add_co_u32_e32 v138, vcc, s66, v136
	s_nop 1
	v_addc_co_u32_e32 v139, vcc, 0, v137, vcc
	v_add_co_u32_e32 v140, vcc, 0xc1000, v136
	s_nop 1
	v_addc_co_u32_e32 v141, vcc, 0, v137, vcc
	v_add_co_u32_e32 v142, vcc, 0xc2000, v136
	s_nop 1
	v_addc_co_u32_e32 v143, vcc, 0, v137, vcc
	v_add_co_u32_e32 v144, vcc, 0xc3000, v136
	s_nop 1
	v_addc_co_u32_e32 v145, vcc, 0, v137, vcc
	global_load_dwordx2 v[176:177], v[138:139], off
	global_load_dwordx2 v[178:179], v[140:141], off
	global_load_dwordx2 v[172:173], v[142:143], off
	global_load_dwordx2 v[174:175], v[144:145], off
	v_add_co_u32_e32 v138, vcc, s19, v136
	s_mov_b32 s19, 0x240000
	s_nop 0
	v_addc_co_u32_e32 v139, vcc, 0, v137, vcc
	v_add_co_u32_e32 v140, vcc, 0x201000, v136
	s_nop 1
	v_addc_co_u32_e32 v141, vcc, 0, v137, vcc
	v_add_co_u32_e32 v142, vcc, 0x202000, v136
	s_nop 1
	v_addc_co_u32_e32 v143, vcc, 0, v137, vcc
	v_add_co_u32_e32 v144, vcc, 0x203000, v136
	s_nop 1
	v_addc_co_u32_e32 v145, vcc, 0, v137, vcc
	global_load_dwordx2 v[168:169], v[138:139], off
	global_load_dwordx2 v[170:171], v[140:141], off
	global_load_dwordx2 v[164:165], v[142:143], off
	global_load_dwordx2 v[166:167], v[144:145], off
	v_add_co_u32_e32 v138, vcc, s19, v136
	s_mov_b32 s19, 0x280000
	s_nop 0
	v_addc_co_u32_e32 v139, vcc, 0, v137, vcc
	v_add_co_u32_e32 v140, vcc, 0x241000, v136
	s_nop 1
	v_addc_co_u32_e32 v141, vcc, 0, v137, vcc
	v_add_co_u32_e32 v142, vcc, 0x242000, v136
	s_nop 1
	v_addc_co_u32_e32 v143, vcc, 0, v137, vcc
	v_add_co_u32_e32 v144, vcc, 0x243000, v136
	s_nop 1
	v_addc_co_u32_e32 v145, vcc, 0, v137, vcc
	global_load_dwordx2 v[158:159], v[138:139], off
	global_load_dwordx2 v[160:161], v[140:141], off
	global_load_dwordx2 v[154:155], v[142:143], off
	global_load_dwordx2 v[156:157], v[144:145], off
	v_add_co_u32_e32 v138, vcc, s19, v136
	s_mov_b32 s19, 0x2c0000
	s_nop 0
	v_addc_co_u32_e32 v139, vcc, 0, v137, vcc
	v_add_co_u32_e32 v140, vcc, 0x281000, v136
	s_nop 1
	v_addc_co_u32_e32 v141, vcc, 0, v137, vcc
	v_add_co_u32_e32 v142, vcc, 0x282000, v136
	s_nop 1
	v_addc_co_u32_e32 v143, vcc, 0, v137, vcc
	v_add_co_u32_e32 v146, vcc, 0x283000, v136
	s_nop 1
	v_addc_co_u32_e32 v147, vcc, 0, v137, vcc
	global_load_dwordx2 v[150:151], v[138:139], off
	global_load_dwordx2 v[152:153], v[140:141], off
	global_load_dwordx2 v[144:145], v[142:143], off
	s_nop 0
	global_load_dwordx2 v[146:147], v[146:147], off
	v_add_co_u32_e32 v138, vcc, s19, v136
	s_nop 1
	v_addc_co_u32_e32 v139, vcc, 0, v137, vcc
	v_add_co_u32_e32 v142, vcc, 0x2c1000, v136
	s_nop 1
	v_addc_co_u32_e32 v143, vcc, 0, v137, vcc
	v_add_co_u32_e32 v204, vcc, 0x2c2000, v136
	s_nop 1
	v_addc_co_u32_e32 v205, vcc, 0, v137, vcc
	v_add_co_u32_e32 v206, vcc, 0x2c3000, v136
	s_nop 1
	v_addc_co_u32_e32 v207, vcc, 0, v137, vcc
	global_load_dwordx2 v[140:141], v[138:139], off
	s_nop 0
	global_load_dwordx2 v[142:143], v[142:143], off
	s_nop 0
	global_load_dwordx2 v[136:137], v[204:205], off
	global_load_dwordx2 v[138:139], v[206:207], off
	v_mul_f32_e32 v126, 0xbfb8aa3b, v126
	v_mul_f32_e32 v122, 0xbfb8aa3b, v122
	v_exp_f32_e32 v126, v126
	v_exp_f32_e32 v122, v122
	v_mul_f32_e32 v123, 0xbfb8aa3b, v123
	v_exp_f32_e32 v123, v123
	v_add_f32_e32 v126, 1.0, v126
	v_add_f32_e32 v122, 1.0, v122
	v_rcp_f32_e32 v206, v126
	v_mul_f32_e32 v126, 0xbfb8aa3b, v128
	v_rcp_f32_e32 v207, v122
	v_add_f32_e32 v122, 1.0, v123
	v_mul_f32_e32 v123, 0xbfb8aa3b, v124
	v_mul_f32_e32 v118, 0xbfb8aa3b, v118
	v_mul_f32_e32 v114, 0xbfb8aa3b, v114
	v_exp_f32_e32 v126, v126
	v_mul_f32_e32 v128, 0xbfb8aa3b, v129
	v_exp_f32_e32 v123, v123
	v_mul_f32_e32 v124, 0xbfb8aa3b, v125
	v_exp_f32_e32 v118, v118
	v_mul_f32_e32 v119, 0xbfb8aa3b, v119
	v_exp_f32_e32 v114, v114
	v_mul_f32_e32 v115, 0xbfb8aa3b, v115
	v_exp_f32_e32 v129, v128
	v_exp_f32_e32 v124, v124
	v_exp_f32_e32 v119, v119
	v_exp_f32_e32 v115, v115
	v_mul_f32_e32 v127, 0xbfb8aa3b, v127
	v_add_f32_e32 v126, 1.0, v126
	v_rcp_f32_e32 v205, v122
	v_add_f32_e32 v122, 1.0, v123
	v_add_f32_e32 v118, 1.0, v118
	v_add_f32_e32 v114, 1.0, v114
	v_exp_f32_e32 v127, v127
	v_rcp_f32_e32 v128, v126
	v_add_f32_e32 v126, 1.0, v129
	v_rcp_f32_e32 v129, v122
	v_add_f32_e32 v122, 1.0, v124
	v_rcp_f32_e32 v124, v118
	v_add_f32_e32 v118, 1.0, v119
	v_mul_f32_e32 v119, 0xbfb8aa3b, v120
	v_rcp_f32_e32 v125, v114
	v_add_f32_e32 v114, 1.0, v115
	v_mul_f32_e32 v115, 0xbfb8aa3b, v116
	v_mul_f32_e32 v110, 0xbfb8aa3b, v110
	v_mul_f32_e32 v106, 0xbfb8aa3b, v106
	v_exp_f32_e32 v119, v119
	v_mul_f32_e32 v120, 0xbfb8aa3b, v121
	v_exp_f32_e32 v115, v115
	v_mul_f32_e32 v116, 0xbfb8aa3b, v117
	v_exp_f32_e32 v110, v110
	v_mul_f32_e32 v111, 0xbfb8aa3b, v111
	v_exp_f32_e32 v106, v106
	v_mul_f32_e32 v107, 0xbfb8aa3b, v107
	v_exp_f32_e32 v121, v120
	v_exp_f32_e32 v116, v116
	v_exp_f32_e32 v111, v111
	v_exp_f32_e32 v107, v107
	v_add_f32_e32 v127, 1.0, v127
	v_rcp_f32_e32 v204, v127
	v_rcp_f32_e32 v127, v122
	v_rcp_f32_e32 v122, v118
	v_add_f32_e32 v118, 1.0, v119
	v_rcp_f32_e32 v123, v114
	v_add_f32_e32 v114, 1.0, v115
	v_add_f32_e32 v110, 1.0, v110
	v_add_f32_e32 v106, 1.0, v106
	v_rcp_f32_e32 v120, v118
	v_add_f32_e32 v118, 1.0, v121
	v_rcp_f32_e32 v121, v114
	v_add_f32_e32 v114, 1.0, v116
	v_rcp_f32_e32 v116, v110
	v_add_f32_e32 v110, 1.0, v111
	v_mul_f32_e32 v111, 0xbfb8aa3b, v112
	v_rcp_f32_e32 v117, v106
	v_add_f32_e32 v106, 1.0, v107
	v_mul_f32_e32 v107, 0xbfb8aa3b, v108
	v_exp_f32_e32 v111, v111
	v_mul_f32_e32 v112, 0xbfb8aa3b, v113
	v_exp_f32_e32 v107, v107
	v_mul_f32_e32 v108, 0xbfb8aa3b, v109
	v_mul_f32_e32 v102, 0xbfb8aa3b, v102
	v_exp_f32_e32 v113, v112
	v_exp_f32_e32 v108, v108
	v_exp_f32_e32 v102, v102
	v_mul_f32_e32 v103, 0xbfb8aa3b, v103
	v_exp_f32_e32 v103, v103
	v_rcp_f32_e32 v119, v114
	v_rcp_f32_e32 v114, v110
	v_add_f32_e32 v110, 1.0, v111
	v_rcp_f32_e32 v115, v106
	v_add_f32_e32 v106, 1.0, v107
	v_rcp_f32_e32 v112, v110
	v_add_f32_e32 v110, 1.0, v113
	v_rcp_f32_e32 v113, v106
	v_add_f32_e32 v106, 1.0, v108
	v_add_f32_e32 v102, 1.0, v102
	v_rcp_f32_e32 v111, v106
	v_rcp_f32_e32 v106, v102
	v_add_f32_e32 v102, 1.0, v103
	v_mul_f32_e32 v103, 0xbfb8aa3b, v104
	v_mul_f32_e32 v104, 0xbfb8aa3b, v105
	v_exp_f32_e32 v103, v103
	v_exp_f32_e32 v105, v104
	v_mul_f32_e32 v94, 0xbfb8aa3b, v94
	v_mul_f32_e32 v90, 0xbfb8aa3b, v90
	v_exp_f32_e32 v94, v94
	v_mul_f32_e32 v95, 0xbfb8aa3b, v95
	v_exp_f32_e32 v90, v90
	v_mul_f32_e32 v91, 0xbfb8aa3b, v91
	v_exp_f32_e32 v95, v95
	v_exp_f32_e32 v91, v91
	v_mul_f32_e32 v98, 0xbfb8aa3b, v98
	v_rcp_f32_e32 v104, v102
	v_add_f32_e32 v102, 1.0, v103
	v_add_f32_e32 v103, 1.0, v105
	v_exp_f32_e32 v105, v98
	v_mul_f32_e32 v98, 0xbfb8aa3b, v99
	v_exp_f32_e32 v99, v98
	v_mul_f32_e32 v100, 0xbfb8aa3b, v100
	v_add_f32_e32 v94, 1.0, v94
	v_add_f32_e32 v90, 1.0, v90
	v_exp_f32_e32 v100, v100
	v_mul_f32_e32 v101, 0xbfb8aa3b, v101
	v_rcp_f32_e32 v108, v94
	v_add_f32_e32 v94, 1.0, v95
	v_mul_f32_e32 v95, 0xbfb8aa3b, v96
	v_rcp_f32_e32 v109, v90
	v_add_f32_e32 v90, 1.0, v91
	v_mul_f32_e32 v91, 0xbfb8aa3b, v92
	v_mul_f32_e32 v86, 0xbfb8aa3b, v86
	v_mul_f32_e32 v82, 0xbfb8aa3b, v82
	v_exp_f32_e32 v101, v101
	v_exp_f32_e32 v95, v95
	v_mul_f32_e32 v96, 0xbfb8aa3b, v97
	v_exp_f32_e32 v91, v91
	v_mul_f32_e32 v92, 0xbfb8aa3b, v93
	v_exp_f32_e32 v86, v86
	v_mul_f32_e32 v87, 0xbfb8aa3b, v87
	v_exp_f32_e32 v82, v82
	v_mul_f32_e32 v83, 0xbfb8aa3b, v83
	v_exp_f32_e32 v97, v96
	v_exp_f32_e32 v92, v92
	v_exp_f32_e32 v87, v87
	v_exp_f32_e32 v83, v83
	v_add_f32_e32 v99, 1.0, v99
	v_rcp_f32_e32 v98, v103
	v_add_f32_e32 v103, 1.0, v105
	v_rcp_f32_e32 v105, v99
	v_add_f32_e32 v99, 1.0, v100
	v_rcp_f32_e32 v107, v103
	v_rcp_f32_e32 v103, v99
	v_add_f32_e32 v99, 1.0, v101
	v_rcp_f32_e32 v100, v94
	v_add_f32_e32 v94, 1.0, v95
	v_rcp_f32_e32 v101, v90
	v_add_f32_e32 v90, 1.0, v91
	v_add_f32_e32 v86, 1.0, v86
	v_add_f32_e32 v82, 1.0, v82
	v_rcp_f32_e32 v96, v94
	v_add_f32_e32 v94, 1.0, v97
	v_rcp_f32_e32 v97, v90
	v_add_f32_e32 v90, 1.0, v92
	v_rcp_f32_e32 v92, v86
	v_add_f32_e32 v86, 1.0, v87
	v_mul_f32_e32 v87, 0xbfb8aa3b, v88
	v_rcp_f32_e32 v93, v82
	v_add_f32_e32 v82, 1.0, v83
	v_mul_f32_e32 v83, 0xbfb8aa3b, v84
	v_mul_f32_e32 v78, 0xbfb8aa3b, v78
	v_mul_f32_e32 v74, 0xbfb8aa3b, v74
	v_exp_f32_e32 v87, v87
	v_mul_f32_e32 v88, 0xbfb8aa3b, v89
	v_exp_f32_e32 v83, v83
	v_mul_f32_e32 v84, 0xbfb8aa3b, v85
	v_exp_f32_e32 v78, v78
	v_mul_f32_e32 v79, 0xbfb8aa3b, v79
	v_exp_f32_e32 v74, v74
	v_mul_f32_e32 v75, 0xbfb8aa3b, v75
	v_exp_f32_e32 v89, v88
	v_exp_f32_e32 v84, v84
	v_exp_f32_e32 v79, v79
	v_exp_f32_e32 v75, v75
	v_rcp_f32_e32 v95, v90
	v_rcp_f32_e32 v90, v86
	v_add_f32_e32 v86, 1.0, v87
	v_rcp_f32_e32 v91, v82
	v_add_f32_e32 v82, 1.0, v83
	v_add_f32_e32 v78, 1.0, v78
	v_add_f32_e32 v74, 1.0, v74
	v_rcp_f32_e32 v88, v86
	v_add_f32_e32 v86, 1.0, v89
	v_rcp_f32_e32 v89, v82
	v_add_f32_e32 v82, 1.0, v84
	v_rcp_f32_e32 v84, v78
	v_add_f32_e32 v78, 1.0, v79
	v_mul_f32_e32 v79, 0xbfb8aa3b, v80
	v_rcp_f32_e32 v85, v74
	v_add_f32_e32 v74, 1.0, v75
	v_mul_f32_e32 v75, 0xbfb8aa3b, v76
	v_mul_f32_e32 v70, 0xbfb8aa3b, v70
	v_exp_f32_e32 v79, v79
	v_mul_f32_e32 v80, 0xbfb8aa3b, v81
	v_exp_f32_e32 v75, v75
	v_mul_f32_e32 v76, 0xbfb8aa3b, v77
	v_exp_f32_e32 v70, v70
	v_mul_f32_e32 v71, 0xbfb8aa3b, v71
	v_exp_f32_e32 v81, v80
	v_exp_f32_e32 v76, v76
	v_exp_f32_e32 v71, v71
	v_rcp_f32_e32 v87, v82
	v_rcp_f32_e32 v82, v78
	v_add_f32_e32 v78, 1.0, v79
	v_rcp_f32_e32 v83, v74
	v_add_f32_e32 v74, 1.0, v75
	v_add_f32_e32 v70, 1.0, v70
	v_rcp_f32_e32 v80, v78
	v_add_f32_e32 v78, 1.0, v81
	v_rcp_f32_e32 v81, v74
	v_add_f32_e32 v74, 1.0, v76
	v_rcp_f32_e32 v76, v70
	v_add_f32_e32 v70, 1.0, v71
	v_mul_f32_e32 v71, 0xbfb8aa3b, v72
	v_mul_f32_e32 v72, 0xbfb8aa3b, v73
	v_exp_f32_e32 v71, v71
	v_exp_f32_e32 v72, v72
	v_mul_f32_e32 v62, 0xbfb8aa3b, v62
	v_mul_f32_e32 v58, 0xbfb8aa3b, v58
	v_mul_f32_e32 v66, 0xbfb8aa3b, v66
	v_exp_f32_e32 v62, v62
	v_mul_f32_e32 v63, 0xbfb8aa3b, v63
	v_exp_f32_e32 v58, v58
	v_mul_f32_e32 v59, 0xbfb8aa3b, v59
	v_rcp_f32_e32 v79, v74
	v_rcp_f32_e32 v74, v70
	v_add_f32_e32 v70, 1.0, v71
	v_add_f32_e32 v71, 1.0, v72
	v_exp_f32_e32 v72, v66
	v_exp_f32_e32 v63, v63
	v_exp_f32_e32 v59, v59
	v_mul_f32_e32 v66, 0xbfb8aa3b, v67
	v_exp_f32_e32 v67, v66
	v_mul_f32_e32 v68, 0xbfb8aa3b, v68
	v_add_f32_e32 v62, 1.0, v62
	v_add_f32_e32 v58, 1.0, v58
	v_rcp_f32_e32 v66, v71
	v_add_f32_e32 v71, 1.0, v72
	v_exp_f32_e32 v68, v68
	v_mul_f32_e32 v69, 0xbfb8aa3b, v69
	v_rcp_f32_e32 v72, v62
	v_add_f32_e32 v62, 1.0, v63
	v_mul_f32_e32 v63, 0xbfb8aa3b, v64
	v_rcp_f32_e32 v73, v58
	v_add_f32_e32 v58, 1.0, v59
	v_mul_f32_e32 v59, 0xbfb8aa3b, v60
	v_mul_f32_e32 v54, 0xbfb8aa3b, v54
	v_mul_f32_e32 v50, 0xbfb8aa3b, v50
	v_exp_f32_e32 v69, v69
	v_exp_f32_e32 v63, v63
	v_mul_f32_e32 v64, 0xbfb8aa3b, v65
	v_exp_f32_e32 v59, v59
	v_mul_f32_e32 v60, 0xbfb8aa3b, v61
	v_exp_f32_e32 v54, v54
	v_mul_f32_e32 v55, 0xbfb8aa3b, v55
	v_exp_f32_e32 v50, v50
	v_mul_f32_e32 v51, 0xbfb8aa3b, v51
	v_exp_f32_e32 v65, v64
	v_exp_f32_e32 v60, v60
	v_exp_f32_e32 v55, v55
	v_exp_f32_e32 v51, v51
	v_add_f32_e32 v67, 1.0, v67
	v_rcp_f32_e32 v75, v67
	v_add_f32_e32 v67, 1.0, v68
	v_rcp_f32_e32 v77, v71
	v_rcp_f32_e32 v71, v67
	v_add_f32_e32 v67, 1.0, v69
	v_rcp_f32_e32 v68, v62
	v_add_f32_e32 v62, 1.0, v63
	v_rcp_f32_e32 v69, v58
	v_add_f32_e32 v58, 1.0, v59
	v_add_f32_e32 v54, 1.0, v54
	v_add_f32_e32 v50, 1.0, v50
	v_rcp_f32_e32 v64, v62
	v_add_f32_e32 v62, 1.0, v65
	v_rcp_f32_e32 v65, v58
	v_add_f32_e32 v58, 1.0, v60
	v_rcp_f32_e32 v60, v54
	v_add_f32_e32 v54, 1.0, v55
	v_mul_f32_e32 v55, 0xbfb8aa3b, v56
	v_rcp_f32_e32 v61, v50
	v_add_f32_e32 v50, 1.0, v51
	v_mul_f32_e32 v51, 0xbfb8aa3b, v52
	v_mul_f32_e32 v46, 0xbfb8aa3b, v46
	v_mul_f32_e32 v42, 0xbfb8aa3b, v42
	v_exp_f32_e32 v55, v55
	v_mul_f32_e32 v56, 0xbfb8aa3b, v57
	v_exp_f32_e32 v51, v51
	v_mul_f32_e32 v52, 0xbfb8aa3b, v53
	v_exp_f32_e32 v46, v46
	v_mul_f32_e32 v47, 0xbfb8aa3b, v47
	v_exp_f32_e32 v42, v42
	v_mul_f32_e32 v43, 0xbfb8aa3b, v43
	v_exp_f32_e32 v57, v56
	v_exp_f32_e32 v52, v52
	v_exp_f32_e32 v47, v47
	v_exp_f32_e32 v43, v43
	v_rcp_f32_e32 v63, v58
	v_rcp_f32_e32 v58, v54
	v_add_f32_e32 v54, 1.0, v55
	v_rcp_f32_e32 v59, v50
	v_add_f32_e32 v50, 1.0, v51
	v_add_f32_e32 v46, 1.0, v46
	v_add_f32_e32 v42, 1.0, v42
	v_rcp_f32_e32 v56, v54
	v_add_f32_e32 v54, 1.0, v57
	v_rcp_f32_e32 v57, v50
	v_add_f32_e32 v50, 1.0, v52
	v_rcp_f32_e32 v52, v46
	v_add_f32_e32 v46, 1.0, v47
	v_mul_f32_e32 v47, 0xbfb8aa3b, v48
	v_rcp_f32_e32 v53, v42
	v_add_f32_e32 v42, 1.0, v43
	v_mul_f32_e32 v43, 0xbfb8aa3b, v44
	v_exp_f32_e32 v47, v47
	v_mul_f32_e32 v48, 0xbfb8aa3b, v49
	v_exp_f32_e32 v43, v43
	v_mul_f32_e32 v44, 0xbfb8aa3b, v45
	v_mul_f32_e32 v38, 0xbfb8aa3b, v38
	v_exp_f32_e32 v49, v48
	v_exp_f32_e32 v44, v44
	v_exp_f32_e32 v38, v38
	v_mul_f32_e32 v39, 0xbfb8aa3b, v39
	v_exp_f32_e32 v39, v39
	v_rcp_f32_e32 v55, v50
	v_rcp_f32_e32 v50, v46
	v_add_f32_e32 v46, 1.0, v47
	v_rcp_f32_e32 v51, v42
	v_add_f32_e32 v42, 1.0, v43
	v_rcp_f32_e32 v48, v46
	v_add_f32_e32 v46, 1.0, v49
	v_rcp_f32_e32 v49, v42
	v_add_f32_e32 v42, 1.0, v44
	v_add_f32_e32 v38, 1.0, v38
	v_rcp_f32_e32 v47, v42
	v_rcp_f32_e32 v42, v38
	v_add_f32_e32 v38, 1.0, v39
	v_mul_f32_e32 v39, 0xbfb8aa3b, v40
	v_mul_f32_e32 v40, 0xbfb8aa3b, v41
	v_exp_f32_e32 v39, v39
	v_exp_f32_e32 v41, v40
	v_mul_f32_e32 v30, 0xbfb8aa3b, v30
	v_mul_f32_e32 v26, 0xbfb8aa3b, v26
	v_exp_f32_e32 v30, v30
	v_mul_f32_e32 v31, 0xbfb8aa3b, v31
	v_exp_f32_e32 v26, v26
	v_mul_f32_e32 v27, 0xbfb8aa3b, v27
	v_exp_f32_e32 v31, v31
	v_exp_f32_e32 v27, v27
	v_mul_f32_e32 v34, 0xbfb8aa3b, v34
	v_rcp_f32_e32 v40, v38
	v_add_f32_e32 v38, 1.0, v39
	v_add_f32_e32 v39, 1.0, v41
	v_exp_f32_e32 v41, v34
	v_mul_f32_e32 v34, 0xbfb8aa3b, v35
	v_exp_f32_e32 v35, v34
	v_mul_f32_e32 v36, 0xbfb8aa3b, v36
	v_add_f32_e32 v30, 1.0, v30
	v_add_f32_e32 v26, 1.0, v26
	v_exp_f32_e32 v36, v36
	v_mul_f32_e32 v37, 0xbfb8aa3b, v37
	v_rcp_f32_e32 v44, v30
	v_add_f32_e32 v30, 1.0, v31
	v_mul_f32_e32 v31, 0xbfb8aa3b, v32
	v_rcp_f32_e32 v45, v26
	v_add_f32_e32 v26, 1.0, v27
	v_mul_f32_e32 v27, 0xbfb8aa3b, v28
	v_mul_f32_e32 v22, 0xbfb8aa3b, v22
	v_mul_f32_e32 v18, 0xbfb8aa3b, v18
	v_exp_f32_e32 v37, v37
	v_exp_f32_e32 v31, v31
	v_mul_f32_e32 v32, 0xbfb8aa3b, v33
	v_exp_f32_e32 v27, v27
	v_mul_f32_e32 v28, 0xbfb8aa3b, v29
	v_exp_f32_e32 v22, v22
	v_mul_f32_e32 v23, 0xbfb8aa3b, v23
	v_exp_f32_e32 v18, v18
	v_mul_f32_e32 v19, 0xbfb8aa3b, v19
	v_exp_f32_e32 v33, v32
	v_exp_f32_e32 v28, v28
	v_exp_f32_e32 v23, v23
	v_exp_f32_e32 v19, v19
	v_add_f32_e32 v35, 1.0, v35
	v_rcp_f32_e32 v34, v39
	v_add_f32_e32 v39, 1.0, v41
	v_rcp_f32_e32 v41, v35
	v_add_f32_e32 v35, 1.0, v36
	v_rcp_f32_e32 v43, v39
	v_rcp_f32_e32 v39, v35
	v_add_f32_e32 v35, 1.0, v37
	v_rcp_f32_e32 v36, v30
	v_add_f32_e32 v30, 1.0, v31
	v_rcp_f32_e32 v37, v26
	v_add_f32_e32 v26, 1.0, v27
	v_add_f32_e32 v22, 1.0, v22
	v_add_f32_e32 v18, 1.0, v18
	v_rcp_f32_e32 v32, v30
	v_add_f32_e32 v30, 1.0, v33
	v_rcp_f32_e32 v33, v26
	v_add_f32_e32 v26, 1.0, v28
	v_rcp_f32_e32 v28, v22
	v_add_f32_e32 v22, 1.0, v23
	v_mul_f32_e32 v23, 0xbfb8aa3b, v24
	v_rcp_f32_e32 v29, v18
	v_add_f32_e32 v18, 1.0, v19
	v_mul_f32_e32 v19, 0xbfb8aa3b, v20
	v_mul_f32_e32 v12, 0xbfb8aa3b, v12
	v_mul_f32_e32 v8, 0xbfb8aa3b, v8
	v_exp_f32_e32 v23, v23
	v_mul_f32_e32 v24, 0xbfb8aa3b, v25
	v_exp_f32_e32 v19, v19
	v_mul_f32_e32 v20, 0xbfb8aa3b, v21
	v_exp_f32_e32 v12, v12
	v_mul_f32_e32 v13, 0xbfb8aa3b, v13
	v_exp_f32_e32 v8, v8
	v_mul_f32_e32 v9, 0xbfb8aa3b, v9
	v_exp_f32_e32 v25, v24
	v_exp_f32_e32 v20, v20
	v_exp_f32_e32 v13, v13
	v_exp_f32_e32 v9, v9
	v_rcp_f32_e32 v31, v26
	v_rcp_f32_e32 v26, v22
	v_add_f32_e32 v22, 1.0, v23
	v_rcp_f32_e32 v27, v18
	v_add_f32_e32 v18, 1.0, v19
	v_add_f32_e32 v12, 1.0, v12
	v_add_f32_e32 v8, 1.0, v8
	v_rcp_f32_e32 v24, v22
	v_add_f32_e32 v22, 1.0, v25
	v_rcp_f32_e32 v25, v18
	v_add_f32_e32 v18, 1.0, v20
	v_rcp_f32_e32 v20, v12
	v_add_f32_e32 v12, 1.0, v13
	v_mul_f32_e32 v13, 0xbfb8aa3b, v14
	v_rcp_f32_e32 v21, v8
	v_add_f32_e32 v8, 1.0, v9
	v_mul_f32_e32 v9, 0xbfb8aa3b, v10
	v_exp_f32_e32 v13, v13
	v_mul_f32_e32 v14, 0xbfb8aa3b, v15
	v_exp_f32_e32 v9, v9
	v_mul_f32_e32 v10, 0xbfb8aa3b, v11
	v_mul_f32_e32 v4, 0xbfb8aa3b, v4
	v_exp_f32_e32 v15, v14
	v_exp_f32_e32 v10, v10
	v_exp_f32_e32 v4, v4
	v_mul_f32_e32 v5, 0xbfb8aa3b, v5
	v_exp_f32_e32 v5, v5
	v_rcp_f32_e32 v23, v18
	v_rcp_f32_e32 v18, v12
	v_add_f32_e32 v12, 1.0, v13
	v_rcp_f32_e32 v19, v8
	v_add_f32_e32 v8, 1.0, v9
	v_rcp_f32_e32 v14, v12
	v_add_f32_e32 v12, 1.0, v15
	v_rcp_f32_e32 v15, v8
	v_add_f32_e32 v8, 1.0, v10
	v_add_f32_e32 v4, 1.0, v4
	v_rcp_f32_e32 v13, v8
	v_rcp_f32_e32 v8, v4
	v_add_f32_e32 v4, 1.0, v5
	v_mul_f32_e32 v5, 0xbfb8aa3b, v6
	v_mul_f32_e32 v6, 0xbfb8aa3b, v7
	v_exp_f32_e32 v5, v5
	v_exp_f32_e32 v7, v6
	v_mul_f32_e32 v0, 0xbfb8aa3b, v0
	v_rcp_f32_e32 v6, v4
	v_add_f32_e32 v4, 1.0, v5
	v_add_f32_e32 v5, 1.0, v7
	v_exp_f32_e32 v7, v0
	v_mul_f32_e32 v0, 0xbfb8aa3b, v1
	v_exp_f32_e32 v1, v0
	v_mul_f32_e32 v2, 0xbfb8aa3b, v2
	v_exp_f32_e32 v2, v2
	v_mul_f32_e32 v3, 0xbfb8aa3b, v3
	v_exp_f32_e32 v3, v3
	v_add_f32_e32 v1, 1.0, v1
	v_rcp_f32_e32 v0, v5
	v_add_f32_e32 v5, 1.0, v7
	v_rcp_f32_e32 v7, v1
	v_add_f32_e32 v1, 1.0, v2
	v_rcp_f32_e32 v9, v5
	v_rcp_f32_e32 v5, v1
	v_add_f32_e32 v1, 1.0, v3
	v_rcp_f32_e32 v126, v126
	v_rcp_f32_e32 v118, v118
	v_rcp_f32_e32 v110, v110
	v_rcp_f32_e32 v102, v102
	v_rcp_f32_e32 v99, v99
	v_rcp_f32_e32 v94, v94
	v_rcp_f32_e32 v86, v86
	v_rcp_f32_e32 v78, v78
	v_rcp_f32_e32 v70, v70
	v_rcp_f32_e32 v67, v67
	v_rcp_f32_e32 v62, v62
	v_rcp_f32_e32 v54, v54
	v_rcp_f32_e32 v46, v46
	v_rcp_f32_e32 v38, v38
	v_rcp_f32_e32 v35, v35
	v_rcp_f32_e32 v30, v30
	v_rcp_f32_e32 v22, v22
	v_rcp_f32_e32 v12, v12
	v_rcp_f32_e32 v4, v4
	v_rcp_f32_e32 v1, v1
	s_waitcnt vmcnt(0)
	v_lshlrev_b32_e32 v3, 16, v202
	v_lshlrev_b32_e32 v2, 16, v200
	v_pk_mul_f32 v[2:3], v[206:207], v[2:3]
	s_mov_b64 s[28:29], -1
	v_add_f32_e32 v2, 0, v2
	v_add_f32_e32 v10, v2, v3
	v_and_b32_e32 v3, 0xffff0000, v202
	v_and_b32_e32 v2, 0xffff0000, v200
	v_pk_mul_f32 v[2:3], v[204:205], v[2:3]
	s_mov_b64 s[92:93], 0x2000
	v_add_f32_e32 v2, 0, v2
	v_add_f32_e32 v11, v2, v3
	v_lshlrev_b32_e32 v3, 16, v203
	v_lshlrev_b32_e32 v2, 16, v201
	v_pk_mul_f32 v[2:3], v[128:129], v[2:3]
	s_mov_b64 s[90:91], s[62:63]
	v_add_f32_e32 v2, 0, v2
	v_add_f32_e32 v128, v2, v3
	v_and_b32_e32 v3, 0xffff0000, v203
	v_and_b32_e32 v2, 0xffff0000, v201
	v_pk_mul_f32 v[2:3], v[126:127], v[2:3]
	s_nop 0
	v_add_f32_e32 v2, 0, v2
	v_add_f32_e32 v126, v2, v3
	v_lshlrev_b32_e32 v3, 16, v198
	v_lshlrev_b32_e32 v2, 16, v196
	v_pk_mul_f32 v[2:3], v[108:109], v[2:3]
	s_nop 0
	v_add_f32_e32 v2, v10, v2
	v_add_f32_e32 v10, v2, v3
	v_and_b32_e32 v3, 0xffff0000, v198
	v_and_b32_e32 v2, 0xffff0000, v196
	v_pk_mul_f32 v[2:3], v[100:101], v[2:3]
	s_nop 0
	v_add_f32_e32 v2, v11, v2
	v_add_f32_e32 v11, v2, v3
	v_lshlrev_b32_e32 v3, 16, v199
	v_lshlrev_b32_e32 v2, 16, v197
	v_pk_mul_f32 v[2:3], v[96:97], v[2:3]
	v_cvt_pk_bf16_f32 v10, v10, v11
	s_nop 0
	v_add_f32_e32 v2, v128, v2
	v_add_f32_e32 v96, v2, v3
	v_and_b32_e32 v3, 0xffff0000, v199
	v_and_b32_e32 v2, 0xffff0000, v197
	v_pk_mul_f32 v[2:3], v[94:95], v[2:3]
	v_lshlrev_b32_e32 v95, 16, v194
	v_add_f32_e32 v2, v126, v2
	v_add_f32_e32 v2, v2, v3
	v_cvt_pk_bf16_f32 v11, v96, v2
	v_lshlrev_b64 v[2:3], 12, v[162:163]
	v_lshl_add_u64 v[2:3], s[72:73], 0, v[2:3]
	v_lshlrev_b32_e32 v94, 16, v192
	v_lshl_add_u64 v[2:3], v[2:3], 0, v[148:149]
	v_pk_mul_f32 v[94:95], v[124:125], v[94:95]
	global_store_dwordx2 v[2:3], v[10:11], off sc1
	v_add_f32_e32 v11, 0, v94
	v_add_f32_e32 v11, v11, v95
	v_and_b32_e32 v95, 0xffff0000, v194
	v_and_b32_e32 v94, 0xffff0000, v192
	v_pk_mul_f32 v[94:95], v[122:123], v[94:95]
	v_or_b32_e32 v10, 16, v162
	v_add_f32_e32 v94, 0, v94
	v_add_f32_e32 v96, v94, v95
	v_lshlrev_b32_e32 v95, 16, v195
	v_lshlrev_b32_e32 v94, 16, v193
	v_pk_mul_f32 v[94:95], v[120:121], v[94:95]
	s_nop 0
	v_add_f32_e32 v94, 0, v94
	v_add_f32_e32 v97, v94, v95
	v_and_b32_e32 v95, 0xffff0000, v195
	v_and_b32_e32 v94, 0xffff0000, v193
	v_pk_mul_f32 v[94:95], v[118:119], v[94:95]
	s_nop 0
	v_add_f32_e32 v94, 0, v94
	v_add_f32_e32 v100, v94, v95
	v_lshlrev_b32_e32 v95, 16, v190
	v_lshlrev_b32_e32 v94, 16, v188
	v_pk_mul_f32 v[92:93], v[92:93], v[94:95]
	s_nop 0
	v_add_f32_e32 v11, v11, v92
	v_add_f32_e32 v94, v11, v93
	v_and_b32_e32 v93, 0xffff0000, v190
	v_and_b32_e32 v92, 0xffff0000, v188
	v_pk_mul_f32 v[90:91], v[90:91], v[92:93]
	s_nop 0
	v_add_f32_e32 v11, v96, v90
	v_add_f32_e32 v92, v11, v91
	v_lshlrev_b32_e32 v91, 16, v191
	v_lshlrev_b32_e32 v90, 16, v189
	v_pk_mul_f32 v[88:89], v[88:89], v[90:91]
	s_nop 0
	v_add_f32_e32 v11, v97, v88
	v_add_f32_e32 v90, v11, v89
	v_and_b32_e32 v89, 0xffff0000, v191
	v_and_b32_e32 v88, 0xffff0000, v189
	v_pk_mul_f32 v[86:87], v[86:87], v[88:89]
	s_nop 0
	v_add_f32_e32 v11, v100, v86
	v_add_f32_e32 v87, v11, v87
	v_ashrrev_i32_e32 v11, 31, v10
	v_lshlrev_b64 v[10:11], 12, v[10:11]
	v_lshl_add_u64 v[10:11], s[72:73], 0, v[10:11]
	v_cvt_pk_bf16_f32 v86, v94, v92
	v_cvt_pk_bf16_f32 v87, v90, v87
	v_lshl_add_u64 v[10:11], v[10:11], 0, v[148:149]
	global_store_dwordx2 v[10:11], v[86:87], off sc1
	v_lshlrev_b32_e32 v87, 16, v186
	v_lshlrev_b32_e32 v86, 16, v184
	v_pk_mul_f32 v[86:87], v[116:117], v[86:87]
	v_or_b32_e32 v10, 32, v162
	v_add_f32_e32 v11, 0, v86
	v_add_f32_e32 v11, v11, v87
	v_and_b32_e32 v87, 0xffff0000, v186
	v_and_b32_e32 v86, 0xffff0000, v184
	v_pk_mul_f32 v[86:87], v[114:115], v[86:87]
	s_nop 0
	v_add_f32_e32 v86, 0, v86
	v_add_f32_e32 v88, v86, v87
	v_lshlrev_b32_e32 v87, 16, v187
	v_lshlrev_b32_e32 v86, 16, v185
	v_pk_mul_f32 v[86:87], v[112:113], v[86:87]
	s_nop 0
	v_add_f32_e32 v86, 0, v86
	v_add_f32_e32 v89, v86, v87
	v_and_b32_e32 v87, 0xffff0000, v187
	v_and_b32_e32 v86, 0xffff0000, v185
	v_pk_mul_f32 v[86:87], v[110:111], v[86:87]
	s_nop 0
	v_add_f32_e32 v86, 0, v86
	v_add_f32_e32 v90, v86, v87
	v_lshlrev_b32_e32 v87, 16, v182
	v_lshlrev_b32_e32 v86, 16, v180
	v_pk_mul_f32 v[84:85], v[84:85], v[86:87]
	s_nop 0
	v_add_f32_e32 v11, v11, v84
	v_add_f32_e32 v86, v11, v85
	v_and_b32_e32 v85, 0xffff0000, v182
	v_and_b32_e32 v84, 0xffff0000, v180
	v_pk_mul_f32 v[82:83], v[82:83], v[84:85]
	s_nop 0
	v_add_f32_e32 v11, v88, v82
	v_add_f32_e32 v84, v11, v83
	v_lshlrev_b32_e32 v83, 16, v183
	v_lshlrev_b32_e32 v82, 16, v181
	v_pk_mul_f32 v[80:81], v[80:81], v[82:83]
	s_nop 0
	v_add_f32_e32 v11, v89, v80
	v_add_f32_e32 v82, v11, v81
	v_and_b32_e32 v81, 0xffff0000, v183
	v_and_b32_e32 v80, 0xffff0000, v181
	v_pk_mul_f32 v[78:79], v[78:79], v[80:81]
	s_nop 0
	v_add_f32_e32 v11, v90, v78
	v_add_f32_e32 v79, v11, v79
	v_ashrrev_i32_e32 v11, 31, v10
	v_lshlrev_b64 v[10:11], 12, v[10:11]
	v_lshl_add_u64 v[10:11], s[72:73], 0, v[10:11]
	v_cvt_pk_bf16_f32 v78, v86, v84
	v_cvt_pk_bf16_f32 v79, v82, v79
	v_lshl_add_u64 v[10:11], v[10:11], 0, v[148:149]
	global_store_dwordx2 v[10:11], v[78:79], off sc1
	v_lshlrev_b32_e32 v79, 16, v178
	v_lshlrev_b32_e32 v78, 16, v176
	v_pk_mul_f32 v[78:79], v[106:107], v[78:79]
	v_or_b32_e32 v10, 48, v162
	v_add_f32_e32 v11, 0, v78
	v_add_f32_e32 v11, v11, v79
	v_and_b32_e32 v79, 0xffff0000, v178
	v_and_b32_e32 v78, 0xffff0000, v176
	v_pk_mul_f32 v[78:79], v[104:105], v[78:79]
	s_nop 0
	v_add_f32_e32 v78, 0, v78
	v_add_f32_e32 v80, v78, v79
	v_lshlrev_b32_e32 v79, 16, v179
	v_lshlrev_b32_e32 v78, 16, v177
	v_pk_mul_f32 v[78:79], v[102:103], v[78:79]
	s_nop 0
	v_add_f32_e32 v78, 0, v78
	v_add_f32_e32 v81, v78, v79
	v_and_b32_e32 v79, 0xffff0000, v179
	v_and_b32_e32 v78, 0xffff0000, v177
	v_pk_mul_f32 v[78:79], v[98:99], v[78:79]
	s_nop 0
	v_add_f32_e32 v78, 0, v78
	v_add_f32_e32 v82, v78, v79
	v_lshlrev_b32_e32 v79, 16, v174
	v_lshlrev_b32_e32 v78, 16, v172
	v_pk_mul_f32 v[76:77], v[76:77], v[78:79]
	s_nop 0
	v_add_f32_e32 v11, v11, v76
	v_add_f32_e32 v78, v11, v77
	v_and_b32_e32 v77, 0xffff0000, v174
	v_and_b32_e32 v76, 0xffff0000, v172
	v_pk_mul_f32 v[74:75], v[74:75], v[76:77]
	s_nop 0
	v_add_f32_e32 v11, v80, v74
	v_add_f32_e32 v76, v11, v75
	v_lshlrev_b32_e32 v75, 16, v175
	v_lshlrev_b32_e32 v74, 16, v173
	v_pk_mul_f32 v[70:71], v[70:71], v[74:75]
	s_nop 0
	v_add_f32_e32 v11, v81, v70
	v_add_f32_e32 v74, v11, v71
	v_and_b32_e32 v71, 0xffff0000, v175
	v_and_b32_e32 v70, 0xffff0000, v173
	v_pk_mul_f32 v[66:67], v[66:67], v[70:71]
	s_nop 0
	v_add_f32_e32 v11, v82, v66
	v_add_f32_e32 v67, v11, v67
	v_ashrrev_i32_e32 v11, 31, v10
	v_lshlrev_b64 v[10:11], 12, v[10:11]
	v_lshl_add_u64 v[10:11], s[72:73], 0, v[10:11]
	v_lshl_add_u64 v[10:11], v[10:11], 0, v[148:149]
	v_cvt_pk_bf16_f32 v66, v78, v76
	v_cvt_pk_bf16_f32 v67, v74, v67
	global_store_dwordx2 v[10:11], v[66:67], off sc1
	v_lshlrev_b32_e32 v11, 16, v170
	v_lshlrev_b32_e32 v10, 16, v168
	v_pk_mul_f32 v[10:11], v[72:73], v[10:11]
	s_nop 0
	v_add_f32_e32 v10, 0, v10
	v_add_f32_e32 v66, v10, v11
	v_and_b32_e32 v11, 0xffff0000, v170
	v_and_b32_e32 v10, 0xffff0000, v168
	v_pk_mul_f32 v[10:11], v[68:69], v[10:11]
	s_nop 0
	v_add_f32_e32 v10, 0, v10
	v_add_f32_e32 v67, v10, v11
	v_lshlrev_b32_e32 v11, 16, v171
	v_lshlrev_b32_e32 v10, 16, v169
	v_pk_mul_f32 v[10:11], v[64:65], v[10:11]
	s_nop 0
	v_add_f32_e32 v10, 0, v10
	v_add_f32_e32 v64, v10, v11
	v_and_b32_e32 v11, 0xffff0000, v171
	v_and_b32_e32 v10, 0xffff0000, v169
	v_pk_mul_f32 v[10:11], v[62:63], v[10:11]
	s_nop 0
	v_add_f32_e32 v10, 0, v10
	v_add_f32_e32 v62, v10, v11
	v_lshlrev_b32_e32 v11, 16, v166
	v_lshlrev_b32_e32 v10, 16, v164
	v_pk_mul_f32 v[10:11], v[44:45], v[10:11]
	s_nop 0
	v_add_f32_e32 v10, v66, v10
	v_add_f32_e32 v44, v10, v11
	v_and_b32_e32 v11, 0xffff0000, v166
	v_and_b32_e32 v10, 0xffff0000, v164
	v_pk_mul_f32 v[10:11], v[36:37], v[10:11]
	s_nop 0
	v_add_f32_e32 v10, v67, v10
	v_add_f32_e32 v36, v10, v11
	v_lshlrev_b32_e32 v11, 16, v167
	v_lshlrev_b32_e32 v10, 16, v165
	v_pk_mul_f32 v[10:11], v[32:33], v[10:11]
	s_nop 0
	v_add_f32_e32 v10, v64, v10
	v_add_f32_e32 v32, v10, v11
	v_and_b32_e32 v11, 0xffff0000, v167
	v_and_b32_e32 v10, 0xffff0000, v165
	v_pk_mul_f32 v[10:11], v[30:31], v[10:11]
	v_add_co_u32_e32 v30, vcc, s64, v2
	v_add_f32_e32 v10, v62, v10
	v_add_f32_e32 v11, v10, v11
	v_cvt_pk_bf16_f32 v10, v44, v36
	v_cvt_pk_bf16_f32 v11, v32, v11
	v_addc_co_u32_e32 v31, vcc, 0, v3, vcc
	global_store_dwordx2 v[30:31], v[10:11], off sc1
	v_lshlrev_b32_e32 v11, 16, v160
	v_lshlrev_b32_e32 v10, 16, v158
	v_pk_mul_f32 v[10:11], v[60:61], v[10:11]
	s_nop 0
	v_add_f32_e32 v10, 0, v10
	v_add_f32_e32 v30, v10, v11
	v_and_b32_e32 v11, 0xffff0000, v160
	v_and_b32_e32 v10, 0xffff0000, v158
	v_pk_mul_f32 v[10:11], v[58:59], v[10:11]
	s_nop 0
	v_add_f32_e32 v10, 0, v10
	v_add_f32_e32 v31, v10, v11
	v_lshlrev_b32_e32 v11, 16, v161
	v_lshlrev_b32_e32 v10, 16, v159
	v_pk_mul_f32 v[10:11], v[56:57], v[10:11]
	s_nop 0
	v_add_f32_e32 v10, 0, v10
	v_add_f32_e32 v32, v10, v11
	v_and_b32_e32 v11, 0xffff0000, v161
	v_and_b32_e32 v10, 0xffff0000, v159
	v_pk_mul_f32 v[10:11], v[54:55], v[10:11]
	s_nop 0
	v_add_f32_e32 v10, 0, v10
	v_add_f32_e32 v33, v10, v11
	v_lshlrev_b32_e32 v11, 16, v156
	v_lshlrev_b32_e32 v10, 16, v154
	v_pk_mul_f32 v[10:11], v[28:29], v[10:11]
	s_nop 0
	v_add_f32_e32 v10, v30, v10
	v_add_f32_e32 v28, v10, v11
	v_and_b32_e32 v11, 0xffff0000, v156
	v_and_b32_e32 v10, 0xffff0000, v154
	v_pk_mul_f32 v[10:11], v[26:27], v[10:11]
	s_nop 0
	v_add_f32_e32 v10, v31, v10
	v_add_f32_e32 v26, v10, v11
	v_lshlrev_b32_e32 v11, 16, v157
	v_lshlrev_b32_e32 v10, 16, v155
	v_pk_mul_f32 v[10:11], v[24:25], v[10:11]
	s_nop 0
	v_add_f32_e32 v10, v32, v10
	v_add_f32_e32 v24, v10, v11
	v_and_b32_e32 v11, 0xffff0000, v157
	v_and_b32_e32 v10, 0xffff0000, v155
	v_pk_mul_f32 v[10:11], v[22:23], v[10:11]
	v_add_co_u32_e32 v22, vcc, s31, v2
	v_add_f32_e32 v10, v33, v10
	v_add_f32_e32 v11, v10, v11
	v_cvt_pk_bf16_f32 v10, v28, v26
	v_cvt_pk_bf16_f32 v11, v24, v11
	v_addc_co_u32_e32 v23, vcc, 0, v3, vcc
	global_store_dwordx2 v[22:23], v[10:11], off sc1
	v_lshlrev_b32_e32 v11, 16, v152
	v_lshlrev_b32_e32 v10, 16, v150
	v_pk_mul_f32 v[10:11], v[52:53], v[10:11]
	s_nop 0
	v_add_f32_e32 v10, 0, v10
	v_add_f32_e32 v22, v10, v11
	v_and_b32_e32 v11, 0xffff0000, v152
	v_and_b32_e32 v10, 0xffff0000, v150
	v_pk_mul_f32 v[10:11], v[50:51], v[10:11]
	s_nop 0
	v_add_f32_e32 v10, 0, v10
	v_add_f32_e32 v23, v10, v11
	v_lshlrev_b32_e32 v11, 16, v153
	v_lshlrev_b32_e32 v10, 16, v151
	v_pk_mul_f32 v[10:11], v[48:49], v[10:11]
	s_nop 0
	v_add_f32_e32 v10, 0, v10
	v_add_f32_e32 v24, v10, v11
	v_and_b32_e32 v11, 0xffff0000, v153
	v_and_b32_e32 v10, 0xffff0000, v151
	v_pk_mul_f32 v[10:11], v[46:47], v[10:11]
	s_nop 0
	v_add_f32_e32 v10, 0, v10
	v_add_f32_e32 v25, v10, v11
	v_lshlrev_b32_e32 v11, 16, v146
	v_lshlrev_b32_e32 v10, 16, v144
	v_pk_mul_f32 v[10:11], v[20:21], v[10:11]
	s_nop 0
	v_add_f32_e32 v10, v22, v10
	v_add_f32_e32 v20, v10, v11
	v_and_b32_e32 v11, 0xffff0000, v146
	v_and_b32_e32 v10, 0xffff0000, v144
	v_pk_mul_f32 v[10:11], v[18:19], v[10:11]
	s_nop 0
	v_add_f32_e32 v10, v23, v10
	v_add_f32_e32 v18, v10, v11
	v_lshlrev_b32_e32 v11, 16, v147
	v_lshlrev_b32_e32 v10, 16, v145
	v_pk_mul_f32 v[10:11], v[14:15], v[10:11]
	s_nop 0
	v_add_f32_e32 v10, v24, v10
	v_add_f32_e32 v14, v10, v11
	v_and_b32_e32 v11, 0xffff0000, v147
	v_and_b32_e32 v10, 0xffff0000, v145
	v_pk_mul_f32 v[10:11], v[12:13], v[10:11]
	v_add_co_u32_e32 v12, vcc, s65, v2
	v_add_f32_e32 v10, v25, v10
	v_add_f32_e32 v11, v10, v11
	v_cvt_pk_bf16_f32 v10, v20, v18
	v_cvt_pk_bf16_f32 v11, v14, v11
	v_addc_co_u32_e32 v13, vcc, 0, v3, vcc
	global_store_dwordx2 v[12:13], v[10:11], off sc1
	v_lshlrev_b32_e32 v11, 16, v142
	v_lshlrev_b32_e32 v10, 16, v140
	v_pk_mul_f32 v[10:11], v[42:43], v[10:11]
	v_add_co_u32_e32 v2, vcc, 0xb0000, v2
	v_add_f32_e32 v10, 0, v10
	v_add_f32_e32 v12, v10, v11
	v_and_b32_e32 v11, 0xffff0000, v142
	v_and_b32_e32 v10, 0xffff0000, v140
	v_pk_mul_f32 v[10:11], v[40:41], v[10:11]
	v_addc_co_u32_e32 v3, vcc, 0, v3, vcc
	v_add_f32_e32 v10, 0, v10
	v_add_f32_e32 v13, v10, v11
	v_lshlrev_b32_e32 v11, 16, v143
	v_lshlrev_b32_e32 v10, 16, v141
	v_pk_mul_f32 v[10:11], v[38:39], v[10:11]
	s_andn2_b64 vcc, exec, s[38:39]
	v_add_f32_e32 v10, 0, v10
	v_add_f32_e32 v14, v10, v11
	v_and_b32_e32 v11, 0xffff0000, v143
	v_and_b32_e32 v10, 0xffff0000, v141
	v_pk_mul_f32 v[10:11], v[34:35], v[10:11]
	s_nop 0
	v_add_f32_e32 v10, 0, v10
	v_add_f32_e32 v15, v10, v11
	v_lshlrev_b32_e32 v11, 16, v138
	v_lshlrev_b32_e32 v10, 16, v136
	v_pk_mul_f32 v[8:9], v[8:9], v[10:11]
	s_nop 0
	v_add_f32_e32 v8, v12, v8
	v_add_f32_e32 v10, v8, v9
	v_and_b32_e32 v9, 0xffff0000, v138
	v_and_b32_e32 v8, 0xffff0000, v136
	v_pk_mul_f32 v[6:7], v[6:7], v[8:9]
	s_nop 0
	v_add_f32_e32 v6, v13, v6
	v_add_f32_e32 v8, v6, v7
	v_lshlrev_b32_e32 v7, 16, v139
	v_lshlrev_b32_e32 v6, 16, v137
	v_pk_mul_f32 v[4:5], v[4:5], v[6:7]
	s_nop 0
	v_add_f32_e32 v4, v14, v4
	v_add_f32_e32 v6, v4, v5
	v_and_b32_e32 v5, 0xffff0000, v139
	v_and_b32_e32 v4, 0xffff0000, v137
	v_pk_mul_f32 v[0:1], v[0:1], v[4:5]
	s_nop 0
	v_add_f32_e32 v0, v15, v0
	v_add_f32_e32 v1, v0, v1
	v_cvt_pk_bf16_f32 v0, v10, v8
	v_cvt_pk_bf16_f32 v1, v6, v1
	global_store_dwordx2 v[2:3], v[0:1], off sc1
	s_cbranch_vccnz .LBB0_713
	s_andn2_b64 vcc, exec, s[0:1]
	s_cbranch_vccnz .LBB0_712
	s_barrier
	s_branch .LBB0_712

.LBB0_797:
	v_lshl_add_u64 v[152:153], v[146:147], 2, v[150:151]
	global_load_dwordx4 v[154:157], v[152:153], off offset:16
	global_load_dwordx4 v[158:161], v[152:153], off
	v_lshlrev_b64 v[162:163], 12, v[148:149]
	s_mov_b64 s[4:5], s[6:7]
	s_mov_b64 s[6:7], 0x20000
	s_mov_b64 s[28:29], 0x10000
	s_waitcnt vmcnt(0)
	v_pk_fma_f32 v[150:151], v[128:129], v[144:145], v[160:161]
	v_pk_fma_f32 v[158:159], v[126:127], v[142:143], v[158:159]
	v_pk_fma_f32 v[160:161], v[124:125], v[140:141], v[156:157]
	v_pk_fma_f32 v[156:157], v[122:123], v[138:139], v[154:155]
	v_cvt_pk_bf16_f32 v154, v158, v159
	v_cvt_pk_bf16_f32 v155, v150, v151
	v_lshl_add_u64 v[150:151], s[4:5], 0, v[162:163]
	v_lshl_add_u64 v[150:151], v[146:147], 1, v[150:151]
	v_cvt_pk_bf16_f32 v156, v156, v157
	v_cvt_pk_bf16_f32 v157, v160, v161
	global_store_dwordx4 v[150:151], v[154:157], off sc1
	global_load_dwordx4 v[154:157], v[152:153], off offset:528
	s_nop 0
	global_load_dwordx4 v[158:161], v[152:153], off offset:512
	v_lshl_add_u64 v[164:165], v[150:151], 0, s[28:29]
	s_mov_b64 s[28:29], 0x40000
	s_waitcnt vmcnt(1)
	v_pk_fma_f32 v[162:163], v[112:113], v[132:133], v[156:157]
	s_waitcnt vmcnt(0)
	v_pk_fma_f32 v[158:159], v[118:119], v[134:135], v[158:159]
	v_pk_fma_f32 v[156:157], v[110:111], v[130:131], v[154:155]
	v_cvt_pk_bf16_f32 v154, v158, v159
	v_pk_fma_f32 v[160:161], v[120:121], v[136:137], v[160:161]
	s_nop 0
	v_cvt_pk_bf16_f32 v155, v160, v161
	v_cvt_pk_bf16_f32 v156, v156, v157
	v_cvt_pk_bf16_f32 v157, v162, v163
	global_store_dwordx4 v[150:151], v[154:157], off offset:256 sc1
	v_lshl_add_u64 v[162:163], v[152:153], 0, s[6:7]
	s_nop 0
	v_add_co_u32_e32 v154, vcc, s17, v152
	s_nop 1
	v_addc_co_u32_e32 v155, vcc, 0, v153, vcc
	global_load_dwordx4 v[154:157], v[154:155], off
	s_nop 0
	global_load_dwordx4 v[158:161], v[162:163], off offset:16
	s_waitcnt vmcnt(1)
	v_pk_fma_f32 v[156:157], v[116:117], v[144:145], v[156:157]
	v_pk_fma_f32 v[154:155], v[114:115], v[142:143], v[154:155]
	s_waitcnt vmcnt(0)
	v_pk_fma_f32 v[158:159], v[106:107], v[138:139], v[158:159]
	v_cvt_pk_bf16_f32 v154, v154, v155
	v_cvt_pk_bf16_f32 v155, v156, v157
	v_pk_fma_f32 v[160:161], v[108:109], v[140:141], v[160:161]
	v_cvt_pk_bf16_f32 v156, v158, v159
	v_add_co_u32_e32 v158, vcc, s67, v150
	v_cvt_pk_bf16_f32 v157, v160, v161
	s_nop 1
	v_addc_co_u32_e32 v159, vcc, 0, v151, vcc
	global_store_dwordx4 v[158:159], v[154:157], off sc1
	global_load_dwordx4 v[154:157], v[162:163], off offset:528
	s_nop 0
	global_load_dwordx4 v[158:161], v[162:163], off offset:512
	s_waitcnt vmcnt(1)
	v_pk_fma_f32 v[162:163], v[96:97], v[132:133], v[156:157]
	s_waitcnt vmcnt(0)
	v_pk_fma_f32 v[158:159], v[102:103], v[134:135], v[158:159]
	v_pk_fma_f32 v[156:157], v[94:95], v[130:131], v[154:155]
	v_cvt_pk_bf16_f32 v154, v158, v159
	v_pk_fma_f32 v[160:161], v[104:105], v[136:137], v[160:161]
	s_nop 0
	v_cvt_pk_bf16_f32 v155, v160, v161
	v_cvt_pk_bf16_f32 v156, v156, v157
	v_cvt_pk_bf16_f32 v157, v162, v163
	global_store_dwordx4 v[164:165], v[154:157], off offset:256 sc1
	v_lshl_add_u64 v[162:163], v[152:153], 0, s[28:29]
	v_lshl_add_u64 v[164:165], v[150:151], 0, s[6:7]
	v_add_co_u32_e32 v154, vcc, s20, v152
	s_mov_b64 s[6:7], 0x60000
	s_nop 0
	v_addc_co_u32_e32 v155, vcc, 0, v153, vcc
	global_load_dwordx4 v[154:157], v[154:155], off
	s_nop 0
	global_load_dwordx4 v[158:161], v[162:163], off offset:16
	s_mov_b64 s[28:29], 0x30000
	s_waitcnt vmcnt(1)
	v_pk_fma_f32 v[156:157], v[100:101], v[144:145], v[156:157]
	v_pk_fma_f32 v[154:155], v[98:99], v[142:143], v[154:155]
	s_waitcnt vmcnt(0)
	v_pk_fma_f32 v[158:159], v[90:91], v[138:139], v[158:159]
	v_cvt_pk_bf16_f32 v154, v154, v155
	v_cvt_pk_bf16_f32 v155, v156, v157
	v_pk_fma_f32 v[160:161], v[92:93], v[140:141], v[160:161]
	v_cvt_pk_bf16_f32 v156, v158, v159
	v_add_co_u32_e32 v158, vcc, s17, v150
	v_cvt_pk_bf16_f32 v157, v160, v161
	s_nop 1
	v_addc_co_u32_e32 v159, vcc, 0, v151, vcc
	global_store_dwordx4 v[158:159], v[154:157], off sc1
	global_load_dwordx4 v[154:157], v[162:163], off offset:528
	s_nop 0
	global_load_dwordx4 v[158:161], v[162:163], off offset:512
	s_waitcnt vmcnt(1)
	v_pk_fma_f32 v[162:163], v[80:81], v[132:133], v[156:157]
	s_waitcnt vmcnt(0)
	v_pk_fma_f32 v[158:159], v[86:87], v[134:135], v[158:159]
	v_pk_fma_f32 v[156:157], v[78:79], v[130:131], v[154:155]
	v_cvt_pk_bf16_f32 v154, v158, v159
	v_pk_fma_f32 v[160:161], v[88:89], v[136:137], v[160:161]
	s_nop 0
	v_cvt_pk_bf16_f32 v155, v160, v161
	v_cvt_pk_bf16_f32 v156, v156, v157
	v_cvt_pk_bf16_f32 v157, v162, v163
	global_store_dwordx4 v[164:165], v[154:157], off offset:256 sc1
	v_lshl_add_u64 v[162:163], v[152:153], 0, s[6:7]
	s_mov_b64 s[6:7], 0x100000
	v_add_co_u32_e32 v154, vcc, s21, v152
	v_lshl_add_u64 v[164:165], v[150:151], 0, s[28:29]
	s_nop 0
	v_addc_co_u32_e32 v155, vcc, 0, v153, vcc
	global_load_dwordx4 v[154:157], v[154:155], off
	s_nop 0
	global_load_dwordx4 v[158:161], v[162:163], off offset:16
	s_mov_b64 s[28:29], 0x80000
	s_waitcnt vmcnt(1)
	v_pk_fma_f32 v[156:157], v[84:85], v[144:145], v[156:157]
	v_pk_fma_f32 v[154:155], v[82:83], v[142:143], v[154:155]
	s_waitcnt vmcnt(0)
	v_pk_fma_f32 v[158:159], v[74:75], v[138:139], v[158:159]
	v_cvt_pk_bf16_f32 v154, v154, v155
	v_cvt_pk_bf16_f32 v155, v156, v157
	v_pk_fma_f32 v[160:161], v[76:77], v[140:141], v[160:161]
	v_cvt_pk_bf16_f32 v156, v158, v159
	v_add_co_u32_e32 v158, vcc, s74, v150
	v_cvt_pk_bf16_f32 v157, v160, v161
	s_nop 1
	v_addc_co_u32_e32 v159, vcc, 0, v151, vcc
	global_store_dwordx4 v[158:159], v[154:157], off sc1
	global_load_dwordx4 v[154:157], v[162:163], off offset:528
	s_nop 0
	global_load_dwordx4 v[158:161], v[162:163], off offset:512
	s_waitcnt vmcnt(1)
	v_pk_fma_f32 v[162:163], v[68:69], v[132:133], v[156:157]
	v_pk_fma_f32 v[156:157], v[66:67], v[130:131], v[154:155]
	s_waitcnt vmcnt(0)
	v_pk_fma_f32 v[160:161], v[72:73], v[136:137], v[160:161]
	v_pk_fma_f32 v[158:159], v[70:71], v[134:135], v[158:159]
	s_nop 0
	v_cvt_pk_bf16_f32 v154, v158, v159
	v_cvt_pk_bf16_f32 v155, v160, v161
	v_cvt_pk_bf16_f32 v156, v156, v157
	v_cvt_pk_bf16_f32 v157, v162, v163
	v_lshl_add_u64 v[162:163], v[152:153], 0, s[6:7]
	s_mov_b32 s6, 0x100000
	global_store_dwordx4 v[164:165], v[154:157], off offset:256 sc1
	v_lshl_add_u64 v[164:165], v[150:151], 0, s[28:29]
	s_mov_b64 s[28:29], 0x90000
	v_add_co_u32_e32 v154, vcc, s6, v152
	s_mov_b64 s[6:7], 0x120000
	s_nop 0
	v_addc_co_u32_e32 v155, vcc, 0, v153, vcc
	global_load_dwordx4 v[154:157], v[154:155], off
	s_nop 0
	global_load_dwordx4 v[158:161], v[162:163], off offset:16
	s_waitcnt vmcnt(1)
	v_pk_fma_f32 v[156:157], v[64:65], v[144:145], v[156:157]
	v_pk_fma_f32 v[154:155], v[62:63], v[142:143], v[154:155]
	s_waitcnt vmcnt(0)
	v_pk_fma_f32 v[158:159], v[58:59], v[138:139], v[158:159]
	v_cvt_pk_bf16_f32 v154, v154, v155
	v_cvt_pk_bf16_f32 v155, v156, v157
	v_pk_fma_f32 v[160:161], v[60:61], v[140:141], v[160:161]
	v_cvt_pk_bf16_f32 v156, v158, v159
	v_add_co_u32_e32 v158, vcc, s64, v150
	v_cvt_pk_bf16_f32 v157, v160, v161
	s_nop 1
	v_addc_co_u32_e32 v159, vcc, 0, v151, vcc
	global_store_dwordx4 v[158:159], v[154:157], off sc1
	global_load_dwordx4 v[154:157], v[162:163], off offset:528
	s_nop 0
	global_load_dwordx4 v[158:161], v[162:163], off offset:512
	s_waitcnt vmcnt(1)
	v_pk_fma_f32 v[162:163], v[48:49], v[132:133], v[156:157]
	v_pk_fma_f32 v[156:157], v[46:47], v[130:131], v[154:155]
	s_waitcnt vmcnt(0)
	v_pk_fma_f32 v[160:161], v[56:57], v[136:137], v[160:161]
	v_pk_fma_f32 v[158:159], v[54:55], v[134:135], v[158:159]
	s_nop 0
	v_cvt_pk_bf16_f32 v154, v158, v159
	v_cvt_pk_bf16_f32 v155, v160, v161
	v_cvt_pk_bf16_f32 v156, v156, v157
	v_cvt_pk_bf16_f32 v157, v162, v163
	v_lshl_add_u64 v[162:163], v[152:153], 0, s[6:7]
	s_mov_b32 s6, 0x120000
	global_store_dwordx4 v[164:165], v[154:157], off offset:256 sc1
	v_lshl_add_u64 v[164:165], v[150:151], 0, s[28:29]
	s_mov_b64 s[28:29], 0xa0000
	v_add_co_u32_e32 v154, vcc, s6, v152
	s_mov_b64 s[6:7], 0x140000
	s_nop 0
	v_addc_co_u32_e32 v155, vcc, 0, v153, vcc
	global_load_dwordx4 v[154:157], v[154:155], off
	s_nop 0
	global_load_dwordx4 v[158:161], v[162:163], off offset:16
	s_waitcnt vmcnt(1)
	v_pk_fma_f32 v[156:157], v[52:53], v[144:145], v[156:157]
	v_pk_fma_f32 v[154:155], v[50:51], v[142:143], v[154:155]
	s_waitcnt vmcnt(0)
	v_pk_fma_f32 v[158:159], v[42:43], v[138:139], v[158:159]
	v_cvt_pk_bf16_f32 v154, v154, v155
	v_cvt_pk_bf16_f32 v155, v156, v157
	v_pk_fma_f32 v[160:161], v[44:45], v[140:141], v[160:161]
	v_cvt_pk_bf16_f32 v156, v158, v159
	v_add_co_u32_e32 v158, vcc, s31, v150
	v_cvt_pk_bf16_f32 v157, v160, v161
	s_nop 1
	v_addc_co_u32_e32 v159, vcc, 0, v151, vcc
	global_store_dwordx4 v[158:159], v[154:157], off sc1
	global_load_dwordx4 v[154:157], v[162:163], off offset:528
	s_nop 0
	global_load_dwordx4 v[158:161], v[162:163], off offset:512
	s_waitcnt vmcnt(1)
	v_pk_fma_f32 v[162:163], v[32:33], v[132:133], v[156:157]
	v_pk_fma_f32 v[156:157], v[30:31], v[130:131], v[154:155]
	s_waitcnt vmcnt(0)
	v_pk_fma_f32 v[160:161], v[40:41], v[136:137], v[160:161]
	v_pk_fma_f32 v[158:159], v[38:39], v[134:135], v[158:159]
	s_nop 0
	v_cvt_pk_bf16_f32 v154, v158, v159
	v_cvt_pk_bf16_f32 v155, v160, v161
	v_cvt_pk_bf16_f32 v156, v156, v157
	v_cvt_pk_bf16_f32 v157, v162, v163
	v_lshl_add_u64 v[162:163], v[152:153], 0, s[6:7]
	s_mov_b32 s6, 0x140000
	global_store_dwordx4 v[164:165], v[154:157], off offset:256 sc1
	v_lshl_add_u64 v[164:165], v[150:151], 0, s[28:29]
	s_mov_b64 s[28:29], 0xb0000
	v_add_co_u32_e32 v154, vcc, s6, v152
	s_mov_b64 s[6:7], 0x160000
	s_nop 0
	v_addc_co_u32_e32 v155, vcc, 0, v153, vcc
	global_load_dwordx4 v[154:157], v[154:155], off
	s_nop 0
	global_load_dwordx4 v[158:161], v[162:163], off offset:16
	s_waitcnt vmcnt(1)
	v_pk_fma_f32 v[156:157], v[36:37], v[144:145], v[156:157]
	v_pk_fma_f32 v[154:155], v[34:35], v[142:143], v[154:155]
	s_waitcnt vmcnt(0)
	v_pk_fma_f32 v[158:159], v[26:27], v[138:139], v[158:159]
	v_cvt_pk_bf16_f32 v154, v154, v155
	v_cvt_pk_bf16_f32 v155, v156, v157
	v_pk_fma_f32 v[160:161], v[28:29], v[140:141], v[160:161]
	v_cvt_pk_bf16_f32 v156, v158, v159
	v_add_co_u32_e32 v158, vcc, s65, v150
	v_cvt_pk_bf16_f32 v157, v160, v161
	s_nop 1
	v_addc_co_u32_e32 v159, vcc, 0, v151, vcc
	global_store_dwordx4 v[158:159], v[154:157], off sc1
	global_load_dwordx4 v[154:157], v[162:163], off offset:528
	s_nop 0
	global_load_dwordx4 v[158:161], v[162:163], off offset:512
	s_waitcnt vmcnt(1)
	v_pk_fma_f32 v[162:163], v[14:15], v[132:133], v[156:157]
	s_waitcnt vmcnt(0)
	v_pk_fma_f32 v[160:161], v[24:25], v[136:137], v[160:161]
	v_pk_fma_f32 v[158:159], v[22:23], v[134:135], v[158:159]
	v_pk_fma_f32 v[156:157], v[12:13], v[130:131], v[154:155]
	v_cvt_pk_bf16_f32 v154, v158, v159
	v_cvt_pk_bf16_f32 v155, v160, v161
	v_lshl_add_u64 v[160:161], v[152:153], 0, s[6:7]
	s_mov_b32 s6, 0x160000
	v_add_co_u32_e32 v152, vcc, s6, v152
	v_cvt_pk_bf16_f32 v156, v156, v157
	v_cvt_pk_bf16_f32 v157, v162, v163
	global_store_dwordx4 v[164:165], v[154:157], off offset:256 sc1
	s_nop 0
	v_addc_co_u32_e32 v153, vcc, 0, v153, vcc
	global_load_dwordx4 v[152:155], v[152:153], off
	s_nop 0
	global_load_dwordx4 v[156:159], v[160:161], off offset:16
	s_mov_b32 s6, 0xb0000
	s_waitcnt vmcnt(1)
	v_pk_fma_f32 v[154:155], v[20:21], v[144:145], v[154:155]
	v_pk_fma_f32 v[152:153], v[18:19], v[142:143], v[152:153]
	s_waitcnt vmcnt(0)
	v_pk_fma_f32 v[158:159], v[10:11], v[140:141], v[158:159]
	v_pk_fma_f32 v[156:157], v[8:9], v[138:139], v[156:157]
	v_cvt_pk_bf16_f32 v152, v152, v153
	v_cvt_pk_bf16_f32 v153, v154, v155
	s_nop 0
	v_cvt_pk_bf16_f32 v154, v156, v157
	v_cvt_pk_bf16_f32 v155, v158, v159
	v_lshl_add_u64 v[158:159], v[150:151], 0, s[28:29]
	v_add_co_u32_e32 v150, vcc, s6, v150
	s_nop 1
	v_addc_co_u32_e32 v151, vcc, 0, v151, vcc
	global_store_dwordx4 v[150:151], v[152:155], off sc1
	global_load_dwordx4 v[150:153], v[160:161], off offset:528
	s_nop 0
	global_load_dwordx4 v[154:157], v[160:161], off offset:512
	s_waitcnt vmcnt(1)
	v_pk_fma_f32 v[160:161], v[2:3], v[132:133], v[152:153]
	v_pk_fma_f32 v[152:153], v[0:1], v[130:131], v[150:151]
	s_waitcnt vmcnt(0)
	v_pk_fma_f32 v[156:157], v[6:7], v[136:137], v[156:157]
	v_pk_fma_f32 v[154:155], v[4:5], v[134:135], v[154:155]
	s_nop 0
	v_cvt_pk_bf16_f32 v150, v154, v155
	v_cvt_pk_bf16_f32 v151, v156, v157
	v_cvt_pk_bf16_f32 v152, v152, v153
	v_cvt_pk_bf16_f32 v153, v160, v161
	global_store_dwordx4 v[158:159], v[150:153], off offset:256 sc1
	s_mov_b64 s[6:7], s[8:9]
	s_branch .LBB0_799
.LBB0_798:
	v_ashrrev_i32_e32 v149, 31, v148
	v_lshlrev_b64 v[148:149], 12, v[148:149]
	v_lshl_add_u64 v[148:149], s[4:5], 0, v[148:149]
	v_lshl_add_u64 v[250:251], v[146:147], 1, v[148:149]
	v_add_co_u32_e32 v252, vcc, 0x10000, v250
	global_load_dwordx4 v[226:229], v[250:251], off
	global_load_dwordx4 v[230:233], v[250:251], off offset:256
	v_addc_co_u32_e32 v253, vcc, 0, v251, vcc
	v_add_co_u32_e32 v216, vcc, 0x20000, v250
	global_load_dwordx4 v[234:237], v[252:253], off
	global_load_dwordx4 v[238:241], v[252:253], off offset:256
	v_addc_co_u32_e32 v217, vcc, 0, v251, vcc
	v_add_co_u32_e32 v204, vcc, 0x30000, v250
	global_load_dwordx4 v[242:245], v[216:217], off
	global_load_dwordx4 v[246:249], v[216:217], off offset:256
	v_addc_co_u32_e32 v205, vcc, 0, v251, vcc
	v_add_co_u32_e32 v202, vcc, 0x80000, v250
	global_load_dwordx4 v[182:185], v[204:205], off
	global_load_dwordx4 v[178:181], v[204:205], off offset:256
	v_addc_co_u32_e32 v203, vcc, 0, v251, vcc
	v_add_co_u32_e32 v200, vcc, 0x90000, v250
	global_load_dwordx4 v[174:177], v[202:203], off
	global_load_dwordx4 v[170:173], v[202:203], off offset:256
	v_addc_co_u32_e32 v201, vcc, 0, v251, vcc
	v_add_co_u32_e32 v198, vcc, 0xa0000, v250
	global_load_dwordx4 v[166:169], v[200:201], off
	global_load_dwordx4 v[162:165], v[200:201], off offset:256
	v_addc_co_u32_e32 v199, vcc, 0, v251, vcc
	v_add_co_u32_e32 v196, vcc, 0xb0000, v250
	global_load_dwordx4 v[158:161], v[198:199], off
	global_load_dwordx4 v[154:157], v[198:199], off offset:256
	v_addc_co_u32_e32 v197, vcc, 0, v251, vcc
	global_load_dwordx4 v[150:153], v[196:197], off
	global_load_dwordx4 v[146:149], v[196:197], off offset:256
	s_waitcnt vmcnt(0)
	v_lshlrev_b32_e32 v225, 16, v226
	v_fmac_f32_e32 v225, v126, v142
	v_and_b32_e32 v126, 0xffff0000, v226
	v_fmac_f32_e32 v126, v127, v143
	v_lshlrev_b32_e32 v127, 16, v227
	v_fmac_f32_e32 v127, v128, v144
	v_and_b32_e32 v128, 0xffff0000, v227
	v_fmac_f32_e32 v128, v129, v145
	v_cvt_pk_bf16_f32 v126, v225, v126
	v_cvt_pk_bf16_f32 v127, v127, v128
	v_lshlrev_b32_e32 v128, 16, v228
	v_fmac_f32_e32 v128, v122, v138
	v_and_b32_e32 v122, 0xffff0000, v228
	v_fmac_f32_e32 v122, v123, v139
	v_cvt_pk_bf16_f32 v128, v128, v122
	v_lshlrev_b32_e32 v122, 16, v229
	v_fmac_f32_e32 v122, v124, v140
	v_and_b32_e32 v123, 0xffff0000, v229
	v_fmac_f32_e32 v123, v125, v141
	v_cvt_pk_bf16_f32 v129, v122, v123
	v_lshlrev_b32_e32 v122, 16, v230
	v_fmac_f32_e32 v122, v118, v134
	v_and_b32_e32 v118, 0xffff0000, v230
	v_fmac_f32_e32 v118, v119, v135
	v_lshlrev_b32_e32 v119, 16, v231
	v_fmac_f32_e32 v119, v120, v136
	v_and_b32_e32 v120, 0xffff0000, v231
	v_fmac_f32_e32 v120, v121, v137
	global_store_dwordx4 v[250:251], v[126:129], off sc1
	v_cvt_pk_bf16_f32 v118, v122, v118
	v_cvt_pk_bf16_f32 v119, v119, v120
	v_lshlrev_b32_e32 v120, 16, v232
	v_fmac_f32_e32 v120, v110, v130
	v_and_b32_e32 v110, 0xffff0000, v232
	v_fmac_f32_e32 v110, v111, v131
	v_cvt_pk_bf16_f32 v120, v120, v110
	v_lshlrev_b32_e32 v110, 16, v233
	v_and_b32_e32 v111, 0xffff0000, v233
	v_fmac_f32_e32 v110, v112, v132
	v_fmac_f32_e32 v111, v113, v133
	v_cvt_pk_bf16_f32 v121, v110, v111
	v_lshlrev_b32_e32 v110, 16, v234
	v_and_b32_e32 v111, 0xffff0000, v234
	v_fmac_f32_e32 v110, v114, v142
	v_fmac_f32_e32 v111, v115, v143
	global_store_dwordx4 v[250:251], v[118:121], off offset:256 sc1
	v_cvt_pk_bf16_f32 v110, v110, v111
	v_lshlrev_b32_e32 v111, 16, v235
	v_and_b32_e32 v112, 0xffff0000, v235
	v_fmac_f32_e32 v111, v116, v144
	v_fmac_f32_e32 v112, v117, v145
	v_cvt_pk_bf16_f32 v111, v111, v112
	v_lshlrev_b32_e32 v112, 16, v236
	v_fmac_f32_e32 v112, v106, v138
	v_and_b32_e32 v106, 0xffff0000, v236
	v_fmac_f32_e32 v106, v107, v139
	v_cvt_pk_bf16_f32 v112, v112, v106
	v_lshlrev_b32_e32 v106, 16, v237
	v_fmac_f32_e32 v106, v108, v140
	v_and_b32_e32 v107, 0xffff0000, v237
	v_fmac_f32_e32 v107, v109, v141
	v_cvt_pk_bf16_f32 v113, v106, v107
	v_lshlrev_b32_e32 v106, 16, v238
	v_fmac_f32_e32 v106, v102, v134
	v_and_b32_e32 v102, 0xffff0000, v238
	v_fmac_f32_e32 v102, v103, v135
	v_lshlrev_b32_e32 v103, 16, v239
	v_fmac_f32_e32 v103, v104, v136
	v_and_b32_e32 v104, 0xffff0000, v239
	v_fmac_f32_e32 v104, v105, v137
	global_store_dwordx4 v[252:253], v[110:113], off sc1
	v_cvt_pk_bf16_f32 v102, v106, v102
	v_cvt_pk_bf16_f32 v103, v103, v104
	v_lshlrev_b32_e32 v104, 16, v240
	v_fmac_f32_e32 v104, v94, v130
	v_and_b32_e32 v94, 0xffff0000, v240
	v_fmac_f32_e32 v94, v95, v131
	v_cvt_pk_bf16_f32 v104, v104, v94
	v_lshlrev_b32_e32 v94, 16, v241
	v_and_b32_e32 v95, 0xffff0000, v241
	v_fmac_f32_e32 v94, v96, v132
	v_fmac_f32_e32 v95, v97, v133
	v_cvt_pk_bf16_f32 v105, v94, v95
	v_lshlrev_b32_e32 v94, 16, v242
	v_and_b32_e32 v95, 0xffff0000, v242
	v_fmac_f32_e32 v94, v98, v142
	v_fmac_f32_e32 v95, v99, v143
	global_store_dwordx4 v[252:253], v[102:105], off offset:256 sc1
	v_cvt_pk_bf16_f32 v94, v94, v95
	v_lshlrev_b32_e32 v95, 16, v243
	v_and_b32_e32 v96, 0xffff0000, v243
	v_fmac_f32_e32 v95, v100, v144
	v_fmac_f32_e32 v96, v101, v145
	v_cvt_pk_bf16_f32 v95, v95, v96
	v_lshlrev_b32_e32 v96, 16, v244
	v_fmac_f32_e32 v96, v90, v138
	v_and_b32_e32 v90, 0xffff0000, v244
	v_fmac_f32_e32 v90, v91, v139
	v_cvt_pk_bf16_f32 v96, v96, v90
	v_lshlrev_b32_e32 v90, 16, v245
	v_fmac_f32_e32 v90, v92, v140
	v_and_b32_e32 v91, 0xffff0000, v245
	v_fmac_f32_e32 v91, v93, v141
	v_cvt_pk_bf16_f32 v97, v90, v91
	v_lshlrev_b32_e32 v90, 16, v246
	v_fmac_f32_e32 v90, v86, v134
	v_and_b32_e32 v86, 0xffff0000, v246
	v_fmac_f32_e32 v86, v87, v135
	v_lshlrev_b32_e32 v87, 16, v247
	v_fmac_f32_e32 v87, v88, v136
	v_and_b32_e32 v88, 0xffff0000, v247
	v_fmac_f32_e32 v88, v89, v137
	global_store_dwordx4 v[216:217], v[94:97], off sc1
	v_cvt_pk_bf16_f32 v86, v90, v86
	v_cvt_pk_bf16_f32 v87, v87, v88
	v_lshlrev_b32_e32 v88, 16, v248
	v_fmac_f32_e32 v88, v78, v130
	v_and_b32_e32 v78, 0xffff0000, v248
	v_fmac_f32_e32 v78, v79, v131
	v_cvt_pk_bf16_f32 v88, v88, v78
	v_lshlrev_b32_e32 v78, 16, v249
	v_and_b32_e32 v79, 0xffff0000, v249
	v_fmac_f32_e32 v78, v80, v132
	v_fmac_f32_e32 v79, v81, v133
	v_cvt_pk_bf16_f32 v89, v78, v79
	v_lshlrev_b32_e32 v78, 16, v182
	v_and_b32_e32 v79, 0xffff0000, v182
	v_fmac_f32_e32 v78, v82, v142
	v_fmac_f32_e32 v79, v83, v143
	global_store_dwordx4 v[216:217], v[86:89], off offset:256 sc1
	v_cvt_pk_bf16_f32 v78, v78, v79
	v_lshlrev_b32_e32 v79, 16, v183
	v_and_b32_e32 v80, 0xffff0000, v183
	v_fmac_f32_e32 v79, v84, v144
	v_fmac_f32_e32 v80, v85, v145
	v_cvt_pk_bf16_f32 v79, v79, v80
	v_lshlrev_b32_e32 v80, 16, v184
	v_fmac_f32_e32 v80, v74, v138
	v_and_b32_e32 v74, 0xffff0000, v184
	v_fmac_f32_e32 v74, v75, v139
	v_cvt_pk_bf16_f32 v80, v80, v74
	v_lshlrev_b32_e32 v74, 16, v185
	v_fmac_f32_e32 v74, v76, v140
	v_and_b32_e32 v75, 0xffff0000, v185
	v_fmac_f32_e32 v75, v77, v141
	v_cvt_pk_bf16_f32 v81, v74, v75
	v_lshlrev_b32_e32 v74, 16, v178
	v_fmac_f32_e32 v74, v70, v134
	v_and_b32_e32 v70, 0xffff0000, v178
	v_fmac_f32_e32 v70, v71, v135
	v_lshlrev_b32_e32 v71, 16, v179
	v_fmac_f32_e32 v71, v72, v136
	v_and_b32_e32 v72, 0xffff0000, v179
	v_fmac_f32_e32 v72, v73, v137
	global_store_dwordx4 v[204:205], v[78:81], off sc1
	v_cvt_pk_bf16_f32 v70, v74, v70
	v_cvt_pk_bf16_f32 v71, v71, v72
	v_lshlrev_b32_e32 v72, 16, v180
	v_fmac_f32_e32 v72, v66, v130
	v_and_b32_e32 v66, 0xffff0000, v180
	v_fmac_f32_e32 v66, v67, v131
	v_cvt_pk_bf16_f32 v72, v72, v66
	v_lshlrev_b32_e32 v66, 16, v181
	v_fmac_f32_e32 v66, v68, v132
	v_and_b32_e32 v67, 0xffff0000, v181
	v_fmac_f32_e32 v67, v69, v133
	v_cvt_pk_bf16_f32 v73, v66, v67
	v_lshlrev_b32_e32 v66, 16, v174
	v_fmac_f32_e32 v66, v62, v142
	v_and_b32_e32 v62, 0xffff0000, v174
	v_fmac_f32_e32 v62, v63, v143
	v_lshlrev_b32_e32 v63, 16, v175
	v_fmac_f32_e32 v63, v64, v144
	v_and_b32_e32 v64, 0xffff0000, v175
	v_fmac_f32_e32 v64, v65, v145
	global_store_dwordx4 v[204:205], v[70:73], off offset:256 sc1
	v_cvt_pk_bf16_f32 v62, v66, v62
	v_cvt_pk_bf16_f32 v63, v63, v64
	v_lshlrev_b32_e32 v64, 16, v176
	v_fmac_f32_e32 v64, v58, v138
	v_and_b32_e32 v58, 0xffff0000, v176
	v_fmac_f32_e32 v58, v59, v139
	v_cvt_pk_bf16_f32 v64, v64, v58
	v_lshlrev_b32_e32 v58, 16, v177
	v_fmac_f32_e32 v58, v60, v140
	v_and_b32_e32 v59, 0xffff0000, v177
	v_fmac_f32_e32 v59, v61, v141
	v_cvt_pk_bf16_f32 v65, v58, v59
	v_lshlrev_b32_e32 v58, 16, v170
	v_fmac_f32_e32 v58, v54, v134
	v_and_b32_e32 v54, 0xffff0000, v170
	v_fmac_f32_e32 v54, v55, v135
	v_lshlrev_b32_e32 v55, 16, v171
	v_fmac_f32_e32 v55, v56, v136
	v_and_b32_e32 v56, 0xffff0000, v171
	v_fmac_f32_e32 v56, v57, v137
	global_store_dwordx4 v[202:203], v[62:65], off sc1
	v_cvt_pk_bf16_f32 v54, v58, v54
	v_cvt_pk_bf16_f32 v55, v55, v56
	v_lshlrev_b32_e32 v56, 16, v172
	v_fmac_f32_e32 v56, v46, v130
	v_and_b32_e32 v46, 0xffff0000, v172
	v_fmac_f32_e32 v46, v47, v131
	v_cvt_pk_bf16_f32 v56, v56, v46
	v_lshlrev_b32_e32 v46, 16, v173
	v_and_b32_e32 v47, 0xffff0000, v173
	v_fmac_f32_e32 v46, v48, v132
	v_fmac_f32_e32 v47, v49, v133
	v_cvt_pk_bf16_f32 v57, v46, v47
	v_lshlrev_b32_e32 v46, 16, v166
	v_and_b32_e32 v47, 0xffff0000, v166
	v_fmac_f32_e32 v46, v50, v142
	v_fmac_f32_e32 v47, v51, v143
	global_store_dwordx4 v[202:203], v[54:57], off offset:256 sc1
	v_cvt_pk_bf16_f32 v46, v46, v47
	v_lshlrev_b32_e32 v47, 16, v167
	v_and_b32_e32 v48, 0xffff0000, v167
	v_fmac_f32_e32 v47, v52, v144
	v_fmac_f32_e32 v48, v53, v145
	v_cvt_pk_bf16_f32 v47, v47, v48
	v_lshlrev_b32_e32 v48, 16, v168
	v_fmac_f32_e32 v48, v42, v138
	v_and_b32_e32 v42, 0xffff0000, v168
	v_fmac_f32_e32 v42, v43, v139
	v_cvt_pk_bf16_f32 v48, v48, v42
	v_lshlrev_b32_e32 v42, 16, v169
	v_fmac_f32_e32 v42, v44, v140
	v_and_b32_e32 v43, 0xffff0000, v169
	v_fmac_f32_e32 v43, v45, v141
	v_cvt_pk_bf16_f32 v49, v42, v43
	v_lshlrev_b32_e32 v42, 16, v162
	v_fmac_f32_e32 v42, v38, v134
	v_and_b32_e32 v38, 0xffff0000, v162
	v_fmac_f32_e32 v38, v39, v135
	v_lshlrev_b32_e32 v39, 16, v163
	v_fmac_f32_e32 v39, v40, v136
	v_and_b32_e32 v40, 0xffff0000, v163
	v_fmac_f32_e32 v40, v41, v137
	global_store_dwordx4 v[200:201], v[46:49], off sc1
	v_cvt_pk_bf16_f32 v38, v42, v38
	v_cvt_pk_bf16_f32 v39, v39, v40
	v_lshlrev_b32_e32 v40, 16, v164
	v_fmac_f32_e32 v40, v30, v130
	v_and_b32_e32 v30, 0xffff0000, v164
	v_fmac_f32_e32 v30, v31, v131
	v_cvt_pk_bf16_f32 v40, v40, v30
	v_lshlrev_b32_e32 v30, 16, v165
	v_and_b32_e32 v31, 0xffff0000, v165
	v_fmac_f32_e32 v30, v32, v132
	v_fmac_f32_e32 v31, v33, v133
	v_cvt_pk_bf16_f32 v41, v30, v31
	v_lshlrev_b32_e32 v30, 16, v158
	v_and_b32_e32 v31, 0xffff0000, v158
	v_fmac_f32_e32 v30, v34, v142
	v_fmac_f32_e32 v31, v35, v143
	global_store_dwordx4 v[200:201], v[38:41], off offset:256 sc1
	v_cvt_pk_bf16_f32 v30, v30, v31
	v_lshlrev_b32_e32 v31, 16, v159
	v_and_b32_e32 v32, 0xffff0000, v159
	v_fmac_f32_e32 v31, v36, v144
	v_fmac_f32_e32 v32, v37, v145
	v_cvt_pk_bf16_f32 v31, v31, v32
	v_lshlrev_b32_e32 v32, 16, v160
	v_fmac_f32_e32 v32, v26, v138
	v_and_b32_e32 v26, 0xffff0000, v160
	v_fmac_f32_e32 v26, v27, v139
	v_cvt_pk_bf16_f32 v32, v32, v26
	v_lshlrev_b32_e32 v26, 16, v161
	v_fmac_f32_e32 v26, v28, v140
	v_and_b32_e32 v27, 0xffff0000, v161
	v_fmac_f32_e32 v27, v29, v141
	v_cvt_pk_bf16_f32 v33, v26, v27
	v_lshlrev_b32_e32 v26, 16, v154
	v_fmac_f32_e32 v26, v22, v134
	v_and_b32_e32 v22, 0xffff0000, v154
	v_fmac_f32_e32 v22, v23, v135
	v_lshlrev_b32_e32 v23, 16, v155
	v_fmac_f32_e32 v23, v24, v136
	v_and_b32_e32 v24, 0xffff0000, v155
	v_fmac_f32_e32 v24, v25, v137
	global_store_dwordx4 v[198:199], v[30:33], off sc1
	v_cvt_pk_bf16_f32 v22, v26, v22
	v_cvt_pk_bf16_f32 v23, v23, v24
	v_lshlrev_b32_e32 v24, 16, v156
	v_fmac_f32_e32 v24, v12, v130
	v_and_b32_e32 v12, 0xffff0000, v156
	v_fmac_f32_e32 v12, v13, v131
	v_cvt_pk_bf16_f32 v24, v24, v12
	v_lshlrev_b32_e32 v12, 16, v157
	v_and_b32_e32 v13, 0xffff0000, v157
	v_fmac_f32_e32 v12, v14, v132
	v_fmac_f32_e32 v13, v15, v133
	v_cvt_pk_bf16_f32 v25, v12, v13
	v_lshlrev_b32_e32 v12, 16, v150
	v_and_b32_e32 v13, 0xffff0000, v150
	v_fmac_f32_e32 v12, v18, v142
	v_fmac_f32_e32 v13, v19, v143
	global_store_dwordx4 v[198:199], v[22:25], off offset:256 sc1
	v_cvt_pk_bf16_f32 v12, v12, v13
	v_lshlrev_b32_e32 v13, 16, v151
	v_and_b32_e32 v14, 0xffff0000, v151
	v_fmac_f32_e32 v13, v20, v144
	v_fmac_f32_e32 v14, v21, v145
	v_cvt_pk_bf16_f32 v13, v13, v14
	v_lshlrev_b32_e32 v14, 16, v152
	v_fmac_f32_e32 v14, v8, v138
	v_and_b32_e32 v8, 0xffff0000, v152
	v_fmac_f32_e32 v8, v9, v139
	v_cvt_pk_bf16_f32 v14, v14, v8
	v_lshlrev_b32_e32 v8, 16, v153
	v_fmac_f32_e32 v8, v10, v140
	v_and_b32_e32 v9, 0xffff0000, v153
	v_fmac_f32_e32 v9, v11, v141
	v_cvt_pk_bf16_f32 v15, v8, v9
	v_lshlrev_b32_e32 v8, 16, v146
	v_fmac_f32_e32 v8, v4, v134
	v_and_b32_e32 v4, 0xffff0000, v146
	v_fmac_f32_e32 v4, v5, v135
	v_lshlrev_b32_e32 v5, 16, v147
	v_fmac_f32_e32 v5, v6, v136
	v_and_b32_e32 v6, 0xffff0000, v147
	v_fmac_f32_e32 v6, v7, v137
	global_store_dwordx4 v[196:197], v[12:15], off sc1
	v_cvt_pk_bf16_f32 v4, v8, v4
	v_cvt_pk_bf16_f32 v5, v5, v6
	v_lshlrev_b32_e32 v6, 16, v148
	v_fmac_f32_e32 v6, v0, v130
	v_and_b32_e32 v0, 0xffff0000, v148
	v_fmac_f32_e32 v0, v1, v131
	v_cvt_pk_bf16_f32 v6, v6, v0
	v_lshlrev_b32_e32 v0, 16, v149
	v_and_b32_e32 v1, 0xffff0000, v149
	v_fmac_f32_e32 v0, v2, v132
	v_fmac_f32_e32 v1, v3, v133
	v_cvt_pk_bf16_f32 v7, v0, v1
	global_store_dwordx4 v[196:197], v[4:7], off offset:256 sc1

.LBB0_923:
	v_mul_f32_e32 v145, 0xbfb8aa3b, v126
	v_exp_f32_e32 v145, v145
	v_lshl_or_b32 v146, s85, 7, v142
	v_lshl_add_u32 v144, s44, 8, v140
	v_ashrrev_i32_e32 v147, 31, v146
	v_add_f32_e32 v145, 1.0, v145
	v_rcp_f32_e32 v145, v145
	s_andn2_b64 vcc, exec, s[38:39]
	s_mov_b64 s[92:93], 0x2000
	s_mov_b64 s[90:91], s[62:63]
	v_mul_f32_e32 v126, v126, v145
	v_mul_f32_e32 v122, v126, v122
	v_mul_f32_e32 v126, 0xbfb8aa3b, v127
	v_exp_f32_e32 v126, v126
	s_nop 0
	v_add_f32_e32 v126, 1.0, v126
	v_rcp_f32_e32 v126, v126
	s_nop 0
	v_mul_f32_e32 v126, v127, v126
	v_mul_f32_e32 v123, v126, v123
	v_mul_f32_e32 v126, 0xbfb8aa3b, v128
	v_exp_f32_e32 v126, v126
	s_nop 0
	v_add_f32_e32 v126, 1.0, v126
	v_rcp_f32_e32 v126, v126
	s_nop 0
	v_mul_f32_e32 v126, v128, v126
	v_mul_f32_e32 v124, v126, v124
	v_mul_f32_e32 v126, 0xbfb8aa3b, v129
	v_exp_f32_e32 v126, v126
	s_nop 0
	v_add_f32_e32 v126, 1.0, v126
	v_rcp_f32_e32 v126, v126
	s_nop 0
	v_mul_f32_e32 v126, v129, v126
	v_mul_f32_e32 v125, v126, v125
	v_mul_f32_e32 v126, 0xbfb8aa3b, v118
	v_exp_f32_e32 v126, v126
	s_nop 0
	v_add_f32_e32 v126, 1.0, v126
	v_rcp_f32_e32 v126, v126
	s_nop 0
	v_mul_f32_e32 v118, v118, v126
	v_mul_f32_e32 v114, v118, v114
	v_mul_f32_e32 v118, 0xbfb8aa3b, v119
	v_exp_f32_e32 v118, v118
	s_nop 0
	v_add_f32_e32 v118, 1.0, v118
	v_rcp_f32_e32 v118, v118
	s_nop 0
	v_mul_f32_e32 v118, v119, v118
	v_mul_f32_e32 v115, v118, v115
	v_mul_f32_e32 v118, 0xbfb8aa3b, v120
	v_exp_f32_e32 v118, v118
	s_nop 0
	v_add_f32_e32 v118, 1.0, v118
	v_rcp_f32_e32 v118, v118
	s_nop 0
	v_mul_f32_e32 v118, v120, v118
	v_mul_f32_e32 v116, v118, v116
	v_mul_f32_e32 v118, 0xbfb8aa3b, v121
	v_exp_f32_e32 v118, v118
	s_nop 0
	v_add_f32_e32 v118, 1.0, v118
	v_rcp_f32_e32 v118, v118
	s_nop 0
	v_mul_f32_e32 v118, v121, v118
	v_mul_f32_e32 v117, v118, v117
	v_cvt_pk_bf16_f32 v118, v122, v123
	v_cvt_pk_bf16_f32 v119, v124, v125
	v_cvt_pk_bf16_f32 v120, v114, v115
	v_mov_b64_e32 v[114:115], s[70:71]
	v_cvt_pk_bf16_f32 v121, v116, v117
	v_mad_i64_i32 v[122:123], s[28:29], v144, s76, v[114:115]
	v_lshlrev_b64 v[116:117], 1, v[146:147]
	v_lshl_add_u64 v[122:123], v[122:123], 0, v[116:117]
	global_store_dwordx4 v[122:123], v[118:121], off sc1
	s_nop 1
	v_mul_f32_e32 v118, 0xbfb8aa3b, v110
	v_exp_f32_e32 v118, v118
	s_nop 0
	v_add_f32_e32 v118, 1.0, v118
	v_rcp_f32_e32 v118, v118
	s_nop 0
	v_mul_f32_e32 v110, v110, v118
	v_mul_f32_e32 v106, v110, v106
	v_mul_f32_e32 v110, 0xbfb8aa3b, v111
	v_exp_f32_e32 v110, v110
	s_nop 0
	v_add_f32_e32 v110, 1.0, v110
	v_rcp_f32_e32 v110, v110
	s_nop 0
	v_mul_f32_e32 v110, v111, v110
	v_mul_f32_e32 v107, v110, v107
	v_mul_f32_e32 v110, 0xbfb8aa3b, v112
	v_exp_f32_e32 v110, v110
	s_nop 0
	v_add_f32_e32 v110, 1.0, v110
	v_rcp_f32_e32 v110, v110
	s_nop 0
	v_mul_f32_e32 v110, v112, v110
	v_mul_f32_e32 v108, v110, v108
	v_mul_f32_e32 v110, 0xbfb8aa3b, v113
	v_exp_f32_e32 v110, v110
	s_nop 0
	v_add_f32_e32 v110, 1.0, v110
	v_rcp_f32_e32 v110, v110
	s_nop 0
	v_mul_f32_e32 v110, v113, v110
	v_mul_f32_e32 v109, v110, v109
	v_mul_f32_e32 v110, 0xbfb8aa3b, v102
	v_exp_f32_e32 v110, v110
	s_nop 0
	v_add_f32_e32 v110, 1.0, v110
	v_rcp_f32_e32 v110, v110
	s_nop 0
	v_mul_f32_e32 v102, v102, v110
	v_mul_f32_e32 v102, v102, v98
	v_mul_f32_e32 v98, 0xbfb8aa3b, v103
	v_exp_f32_e32 v98, v98
	s_nop 0
	v_add_f32_e32 v98, 1.0, v98
	v_rcp_f32_e32 v98, v98
	s_nop 0
	v_mul_f32_e32 v98, v103, v98
	v_mul_f32_e32 v103, v98, v99
	v_mul_f32_e32 v98, 0xbfb8aa3b, v104
	v_exp_f32_e32 v98, v98
	s_nop 0
	v_add_f32_e32 v98, 1.0, v98
	v_rcp_f32_e32 v98, v98
	s_nop 0
	v_mul_f32_e32 v98, v104, v98
	v_mul_f32_e32 v104, v98, v100
	v_mul_f32_e32 v98, 0xbfb8aa3b, v105
	v_exp_f32_e32 v98, v98
	s_nop 0
	v_add_f32_e32 v98, 1.0, v98
	v_rcp_f32_e32 v98, v98
	s_nop 0
	v_mul_f32_e32 v98, v105, v98
	v_mul_f32_e32 v101, v98, v101
	v_cvt_pk_bf16_f32 v98, v106, v107
	v_cvt_pk_bf16_f32 v99, v108, v109
	v_cvt_pk_bf16_f32 v100, v102, v103
	v_or_b32_e32 v102, 16, v144
	v_mad_i64_i32 v[102:103], s[28:29], v102, s76, v[114:115]
	v_lshl_add_u64 v[102:103], v[102:103], 0, v[116:117]
	v_cvt_pk_bf16_f32 v101, v104, v101
	global_store_dwordx4 v[102:103], v[98:101], off sc1
	s_nop 1
	v_mul_f32_e32 v98, 0xbfb8aa3b, v94
	v_exp_f32_e32 v98, v98
	s_nop 0
	v_add_f32_e32 v98, 1.0, v98
	v_rcp_f32_e32 v98, v98
	s_nop 0
	v_mul_f32_e32 v94, v94, v98
	v_mul_f32_e32 v90, v94, v90
	v_mul_f32_e32 v94, 0xbfb8aa3b, v95
	v_exp_f32_e32 v94, v94
	s_nop 0
	v_add_f32_e32 v94, 1.0, v94
	v_rcp_f32_e32 v94, v94
	s_nop 0
	v_mul_f32_e32 v94, v95, v94
	v_mul_f32_e32 v91, v94, v91
	v_mul_f32_e32 v94, 0xbfb8aa3b, v96
	v_exp_f32_e32 v94, v94
	s_nop 0
	v_add_f32_e32 v94, 1.0, v94
	v_rcp_f32_e32 v94, v94
	s_nop 0
	v_mul_f32_e32 v94, v96, v94
	v_mul_f32_e32 v92, v94, v92
	v_mul_f32_e32 v94, 0xbfb8aa3b, v97
	v_exp_f32_e32 v94, v94
	s_nop 0
	v_add_f32_e32 v94, 1.0, v94
	v_rcp_f32_e32 v94, v94
	s_nop 0
	v_mul_f32_e32 v94, v97, v94
	v_mul_f32_e32 v93, v94, v93
	v_mul_f32_e32 v94, 0xbfb8aa3b, v86
	v_exp_f32_e32 v94, v94
	s_nop 0
	v_add_f32_e32 v94, 1.0, v94
	v_rcp_f32_e32 v94, v94
	s_nop 0
	v_mul_f32_e32 v86, v86, v94
	v_mul_f32_e32 v86, v86, v82
	v_mul_f32_e32 v82, 0xbfb8aa3b, v87
	v_exp_f32_e32 v82, v82
	s_nop 0
	v_add_f32_e32 v82, 1.0, v82
	v_rcp_f32_e32 v82, v82
	s_nop 0
	v_mul_f32_e32 v82, v87, v82
	v_mul_f32_e32 v87, v82, v83
	v_mul_f32_e32 v82, 0xbfb8aa3b, v88
	v_exp_f32_e32 v82, v82
	s_nop 0
	v_add_f32_e32 v82, 1.0, v82
	v_rcp_f32_e32 v82, v82
	s_nop 0
	v_mul_f32_e32 v82, v88, v82
	v_mul_f32_e32 v88, v82, v84
	v_mul_f32_e32 v82, 0xbfb8aa3b, v89
	v_exp_f32_e32 v82, v82
	s_nop 0
	v_add_f32_e32 v82, 1.0, v82
	v_rcp_f32_e32 v82, v82
	s_nop 0
	v_mul_f32_e32 v82, v89, v82
	v_mul_f32_e32 v85, v82, v85
	v_cvt_pk_bf16_f32 v82, v90, v91
	v_cvt_pk_bf16_f32 v83, v92, v93
	v_cvt_pk_bf16_f32 v84, v86, v87
	v_or_b32_e32 v86, 32, v144
	v_mad_i64_i32 v[86:87], s[28:29], v86, s76, v[114:115]
	v_lshl_add_u64 v[86:87], v[86:87], 0, v[116:117]
	v_cvt_pk_bf16_f32 v85, v88, v85
	global_store_dwordx4 v[86:87], v[82:85], off sc1
	s_nop 1
	v_mul_f32_e32 v82, 0xbfb8aa3b, v78
	v_exp_f32_e32 v82, v82
	s_nop 0
	v_add_f32_e32 v82, 1.0, v82
	v_rcp_f32_e32 v82, v82
	s_nop 0
	v_mul_f32_e32 v78, v78, v82
	v_mul_f32_e32 v74, v78, v74
	v_mul_f32_e32 v78, 0xbfb8aa3b, v79
	v_exp_f32_e32 v78, v78
	s_nop 0
	v_add_f32_e32 v78, 1.0, v78
	v_rcp_f32_e32 v78, v78
	s_nop 0
	v_mul_f32_e32 v78, v79, v78
	v_mul_f32_e32 v75, v78, v75
	v_mul_f32_e32 v78, 0xbfb8aa3b, v80
	v_exp_f32_e32 v78, v78
	s_nop 0
	v_add_f32_e32 v78, 1.0, v78
	v_rcp_f32_e32 v78, v78
	s_nop 0
	v_mul_f32_e32 v78, v80, v78
	v_mul_f32_e32 v76, v78, v76
	v_mul_f32_e32 v78, 0xbfb8aa3b, v81
	v_exp_f32_e32 v78, v78
	s_nop 0
	v_add_f32_e32 v78, 1.0, v78
	v_rcp_f32_e32 v78, v78
	s_nop 0
	v_mul_f32_e32 v78, v81, v78
	v_mul_f32_e32 v77, v78, v77
	v_mul_f32_e32 v78, 0xbfb8aa3b, v70
	v_exp_f32_e32 v78, v78
	s_nop 0
	v_add_f32_e32 v78, 1.0, v78
	v_rcp_f32_e32 v78, v78
	s_nop 0
	v_mul_f32_e32 v70, v70, v78
	v_mul_f32_e32 v70, v70, v66
	v_mul_f32_e32 v66, 0xbfb8aa3b, v71
	v_exp_f32_e32 v66, v66
	s_nop 0
	v_add_f32_e32 v66, 1.0, v66
	v_rcp_f32_e32 v66, v66
	s_nop 0
	v_mul_f32_e32 v66, v71, v66
	v_mul_f32_e32 v71, v66, v67
	v_mul_f32_e32 v66, 0xbfb8aa3b, v72
	v_exp_f32_e32 v66, v66
	s_nop 0
	v_add_f32_e32 v66, 1.0, v66
	v_rcp_f32_e32 v66, v66
	s_nop 0
	v_mul_f32_e32 v66, v72, v66
	v_mul_f32_e32 v72, v66, v68
	v_mul_f32_e32 v66, 0xbfb8aa3b, v73
	v_exp_f32_e32 v66, v66
	s_nop 0
	v_add_f32_e32 v66, 1.0, v66
	v_rcp_f32_e32 v66, v66
	s_nop 0
	v_mul_f32_e32 v66, v73, v66
	v_mul_f32_e32 v69, v66, v69
	v_cvt_pk_bf16_f32 v66, v74, v75
	v_cvt_pk_bf16_f32 v67, v76, v77
	v_cvt_pk_bf16_f32 v68, v70, v71
	v_or_b32_e32 v70, 48, v144
	v_mad_i64_i32 v[70:71], s[28:29], v70, s76, v[114:115]
	v_lshl_add_u64 v[70:71], v[70:71], 0, v[116:117]
	v_cvt_pk_bf16_f32 v69, v72, v69
	global_store_dwordx4 v[70:71], v[66:69], off sc1
	s_nop 1
	v_mul_f32_e32 v67, 0xbfb8aa3b, v62
	v_exp_f32_e32 v67, v67
	v_add_u32_e32 v66, 0x80, v144
	v_add_f32_e32 v67, 1.0, v67
	v_rcp_f32_e32 v67, v67
	s_nop 0
	v_mul_f32_e32 v62, v62, v67
	v_mul_f32_e32 v58, v62, v58
	v_mul_f32_e32 v62, 0xbfb8aa3b, v63
	v_exp_f32_e32 v62, v62
	s_nop 0
	v_add_f32_e32 v62, 1.0, v62
	v_rcp_f32_e32 v62, v62
	s_nop 0
	v_mul_f32_e32 v62, v63, v62
	v_mul_f32_e32 v59, v62, v59
	v_mul_f32_e32 v62, 0xbfb8aa3b, v64
	v_exp_f32_e32 v62, v62
	s_nop 0
	v_add_f32_e32 v62, 1.0, v62
	v_rcp_f32_e32 v62, v62
	s_nop 0
	v_mul_f32_e32 v62, v64, v62
	v_mul_f32_e32 v60, v62, v60
	v_mul_f32_e32 v62, 0xbfb8aa3b, v65
	v_exp_f32_e32 v62, v62
	s_nop 0
	v_add_f32_e32 v62, 1.0, v62
	v_rcp_f32_e32 v62, v62
	s_nop 0
	v_mul_f32_e32 v62, v65, v62
	v_mul_f32_e32 v61, v62, v61
	v_mul_f32_e32 v62, 0xbfb8aa3b, v54
	v_exp_f32_e32 v62, v62
	s_nop 0
	v_add_f32_e32 v62, 1.0, v62
	v_rcp_f32_e32 v62, v62
	s_nop 0
	v_mul_f32_e32 v54, v54, v62
	v_mul_f32_e32 v54, v54, v50
	v_mul_f32_e32 v50, 0xbfb8aa3b, v55
	v_exp_f32_e32 v50, v50
	s_nop 0
	v_add_f32_e32 v50, 1.0, v50
	v_rcp_f32_e32 v50, v50
	s_nop 0
	v_mul_f32_e32 v50, v55, v50
	v_mul_f32_e32 v55, v50, v51
	v_mul_f32_e32 v50, 0xbfb8aa3b, v56
	v_exp_f32_e32 v50, v50
	s_nop 0
	v_add_f32_e32 v50, 1.0, v50
	v_rcp_f32_e32 v50, v50
	s_nop 0
	v_mul_f32_e32 v50, v56, v50
	v_mul_f32_e32 v56, v50, v52
	v_mul_f32_e32 v50, 0xbfb8aa3b, v57
	v_exp_f32_e32 v50, v50
	s_nop 0
	v_add_f32_e32 v50, 1.0, v50
	v_rcp_f32_e32 v50, v50
	s_nop 0
	v_mul_f32_e32 v50, v57, v50
	v_mul_f32_e32 v53, v50, v53
	v_cvt_pk_bf16_f32 v50, v58, v59
	v_cvt_pk_bf16_f32 v51, v60, v61
	v_cvt_pk_bf16_f32 v52, v54, v55
	v_mad_i64_i32 v[54:55], s[28:29], v66, s76, v[114:115]
	v_lshl_add_u64 v[54:55], v[54:55], 0, v[116:117]
	v_cvt_pk_bf16_f32 v53, v56, v53
	global_store_dwordx4 v[54:55], v[50:53], off sc1
	s_nop 1
	v_mul_f32_e32 v50, 0xbfb8aa3b, v46
	v_exp_f32_e32 v50, v50
	s_nop 0
	v_add_f32_e32 v50, 1.0, v50
	v_rcp_f32_e32 v50, v50
	s_nop 0
	v_mul_f32_e32 v46, v46, v50
	v_mul_f32_e32 v42, v46, v42
	v_mul_f32_e32 v46, 0xbfb8aa3b, v47
	v_exp_f32_e32 v46, v46
	s_nop 0
	v_add_f32_e32 v46, 1.0, v46
	v_rcp_f32_e32 v46, v46
	s_nop 0
	v_mul_f32_e32 v46, v47, v46
	v_mul_f32_e32 v43, v46, v43
	v_mul_f32_e32 v46, 0xbfb8aa3b, v48
	v_exp_f32_e32 v46, v46
	s_nop 0
	v_add_f32_e32 v46, 1.0, v46
	v_rcp_f32_e32 v46, v46
	s_nop 0
	v_mul_f32_e32 v46, v48, v46
	v_mul_f32_e32 v44, v46, v44
	v_mul_f32_e32 v46, 0xbfb8aa3b, v49
	v_exp_f32_e32 v46, v46
	s_nop 0
	v_add_f32_e32 v46, 1.0, v46
	v_rcp_f32_e32 v46, v46
	s_nop 0
	v_mul_f32_e32 v46, v49, v46
	v_mul_f32_e32 v45, v46, v45
	v_mul_f32_e32 v46, 0xbfb8aa3b, v38
	v_exp_f32_e32 v46, v46
	s_nop 0
	v_add_f32_e32 v46, 1.0, v46
	v_rcp_f32_e32 v46, v46
	s_nop 0
	v_mul_f32_e32 v38, v38, v46
	v_mul_f32_e32 v38, v38, v34
	v_mul_f32_e32 v34, 0xbfb8aa3b, v39
	v_exp_f32_e32 v34, v34
	s_nop 0
	v_add_f32_e32 v34, 1.0, v34
	v_rcp_f32_e32 v34, v34
	s_nop 0
	v_mul_f32_e32 v34, v39, v34
	v_mul_f32_e32 v39, v34, v35
	v_mul_f32_e32 v34, 0xbfb8aa3b, v40
	v_exp_f32_e32 v34, v34
	s_nop 0
	v_add_f32_e32 v34, 1.0, v34
	v_rcp_f32_e32 v34, v34
	s_nop 0
	v_mul_f32_e32 v34, v40, v34
	v_mul_f32_e32 v40, v34, v36
	v_mul_f32_e32 v34, 0xbfb8aa3b, v41
	v_exp_f32_e32 v34, v34
	s_nop 0
	v_add_f32_e32 v34, 1.0, v34
	v_rcp_f32_e32 v34, v34
	s_nop 0
	v_mul_f32_e32 v34, v41, v34
	v_mul_f32_e32 v37, v34, v37
	v_cvt_pk_bf16_f32 v34, v42, v43
	v_cvt_pk_bf16_f32 v35, v44, v45
	v_cvt_pk_bf16_f32 v36, v38, v39
	v_add_u32_e32 v38, 0x90, v144
	v_mad_i64_i32 v[38:39], s[28:29], v38, s76, v[114:115]
	v_lshl_add_u64 v[38:39], v[38:39], 0, v[116:117]
	v_cvt_pk_bf16_f32 v37, v40, v37
	global_store_dwordx4 v[38:39], v[34:37], off sc1
	s_nop 1
	v_mul_f32_e32 v34, 0xbfb8aa3b, v30
	v_exp_f32_e32 v34, v34
	s_nop 0
	v_add_f32_e32 v34, 1.0, v34
	v_rcp_f32_e32 v34, v34
	s_nop 0
	v_mul_f32_e32 v30, v30, v34
	v_mul_f32_e32 v26, v30, v26
	v_mul_f32_e32 v30, 0xbfb8aa3b, v31
	v_exp_f32_e32 v30, v30
	s_nop 0
	v_add_f32_e32 v30, 1.0, v30
	v_rcp_f32_e32 v30, v30
	s_nop 0
	v_mul_f32_e32 v30, v31, v30
	v_mul_f32_e32 v27, v30, v27
	v_mul_f32_e32 v30, 0xbfb8aa3b, v32
	v_exp_f32_e32 v30, v30
	s_nop 0
	v_add_f32_e32 v30, 1.0, v30
	v_rcp_f32_e32 v30, v30
	s_nop 0
	v_mul_f32_e32 v30, v32, v30
	v_mul_f32_e32 v28, v30, v28
	v_mul_f32_e32 v30, 0xbfb8aa3b, v33
	v_exp_f32_e32 v30, v30
	s_nop 0
	v_add_f32_e32 v30, 1.0, v30
	v_rcp_f32_e32 v30, v30
	s_nop 0
	v_mul_f32_e32 v30, v33, v30
	v_mul_f32_e32 v29, v30, v29
	v_mul_f32_e32 v30, 0xbfb8aa3b, v22
	v_exp_f32_e32 v30, v30
	s_nop 0
	v_add_f32_e32 v30, 1.0, v30
	v_rcp_f32_e32 v30, v30
	s_nop 0
	v_mul_f32_e32 v22, v22, v30
	v_mul_f32_e32 v22, v22, v18
	v_mul_f32_e32 v18, 0xbfb8aa3b, v23
	v_exp_f32_e32 v18, v18
	s_nop 0
	v_add_f32_e32 v18, 1.0, v18
	v_rcp_f32_e32 v18, v18
	s_nop 0
	v_mul_f32_e32 v18, v23, v18
	v_mul_f32_e32 v23, v18, v19
	v_mul_f32_e32 v18, 0xbfb8aa3b, v24
	v_exp_f32_e32 v18, v18
	s_nop 0
	v_add_f32_e32 v18, 1.0, v18
	v_rcp_f32_e32 v18, v18
	s_nop 0
	v_mul_f32_e32 v18, v24, v18
	v_mul_f32_e32 v24, v18, v20
	v_mul_f32_e32 v18, 0xbfb8aa3b, v25
	v_exp_f32_e32 v18, v18
	s_nop 0
	v_add_f32_e32 v18, 1.0, v18
	v_rcp_f32_e32 v18, v18
	s_nop 0
	v_mul_f32_e32 v18, v25, v18
	v_mul_f32_e32 v21, v18, v21
	v_cvt_pk_bf16_f32 v18, v26, v27
	v_cvt_pk_bf16_f32 v19, v28, v29
	v_cvt_pk_bf16_f32 v20, v22, v23
	v_add_u32_e32 v22, 0xa0, v144
	v_mad_i64_i32 v[22:23], s[28:29], v22, s76, v[114:115]
	v_lshl_add_u64 v[22:23], v[22:23], 0, v[116:117]
	v_cvt_pk_bf16_f32 v21, v24, v21
	global_store_dwordx4 v[22:23], v[18:21], off sc1
	s_nop 1
	v_mul_f32_e32 v18, 0xbfb8aa3b, v12
	v_exp_f32_e32 v18, v18
	s_nop 0
	v_add_f32_e32 v18, 1.0, v18
	v_rcp_f32_e32 v18, v18
	s_nop 0
	v_mul_f32_e32 v12, v12, v18
	v_mul_f32_e32 v8, v12, v8
	v_mul_f32_e32 v12, 0xbfb8aa3b, v13
	v_exp_f32_e32 v12, v12
	s_nop 0
	v_add_f32_e32 v12, 1.0, v12
	v_rcp_f32_e32 v12, v12
	s_nop 0
	v_mul_f32_e32 v12, v13, v12
	v_mul_f32_e32 v9, v12, v9
	v_mul_f32_e32 v12, 0xbfb8aa3b, v14
	v_exp_f32_e32 v12, v12
	s_nop 0
	v_add_f32_e32 v12, 1.0, v12
	v_rcp_f32_e32 v12, v12
	s_nop 0
	v_mul_f32_e32 v12, v14, v12
	v_mul_f32_e32 v10, v12, v10
	v_mul_f32_e32 v12, 0xbfb8aa3b, v15
	v_exp_f32_e32 v12, v12
	s_nop 0
	v_add_f32_e32 v12, 1.0, v12
	v_rcp_f32_e32 v12, v12
	s_nop 0
	v_mul_f32_e32 v12, v15, v12
	v_mul_f32_e32 v11, v12, v11
	v_mul_f32_e32 v12, 0xbfb8aa3b, v4
	v_exp_f32_e32 v12, v12
	s_nop 0
	v_add_f32_e32 v12, 1.0, v12
	v_rcp_f32_e32 v12, v12
	s_nop 0
	v_mul_f32_e32 v4, v4, v12
	v_mul_f32_e32 v4, v4, v0
	v_mul_f32_e32 v0, 0xbfb8aa3b, v5
	v_exp_f32_e32 v0, v0
	s_nop 0
	v_add_f32_e32 v0, 1.0, v0
	v_rcp_f32_e32 v0, v0
	s_nop 0
	v_mul_f32_e32 v0, v5, v0
	v_mul_f32_e32 v5, v0, v1
	v_mul_f32_e32 v0, 0xbfb8aa3b, v6
	v_exp_f32_e32 v0, v0
	s_nop 0
	v_add_f32_e32 v0, 1.0, v0
	v_rcp_f32_e32 v0, v0
	s_nop 0
	v_mul_f32_e32 v0, v6, v0
	v_mul_f32_e32 v6, v0, v2
	v_mul_f32_e32 v0, 0xbfb8aa3b, v7
	v_exp_f32_e32 v0, v0
	s_nop 0
	v_add_f32_e32 v0, 1.0, v0
	v_rcp_f32_e32 v0, v0
	s_nop 0
	v_mul_f32_e32 v0, v7, v0
	v_mul_f32_e32 v3, v0, v3
	v_cvt_pk_bf16_f32 v0, v8, v9
	v_cvt_pk_bf16_f32 v1, v10, v11
	v_cvt_pk_bf16_f32 v2, v4, v5
	v_add_u32_e32 v4, 0xb0, v144
	v_mad_i64_i32 v[4:5], s[28:29], v4, s76, v[114:115]
	v_lshl_add_u64 v[4:5], v[4:5], 0, v[116:117]
	s_mov_b64 s[28:29], -1
	v_cvt_pk_bf16_f32 v3, v6, v3
	global_store_dwordx4 v[4:5], v[0:3], off sc1
	s_cbranch_vccnz .LBB0_916
	s_andn2_b64 vcc, exec, s[14:15]
	s_cbranch_vccnz .LBB0_915
	s_barrier
	s_branch .LBB0_915

.LBB0_997:
	v_lshl_add_u32 v148, s84, 8, v202
	v_ashrrev_i32_e32 v149, 31, v148
	v_lshl_or_b32 v146, s85, 8, v204
	v_lshlrev_b64 v[148:149], 12, v[148:149]
	v_ashrrev_i32_e32 v147, 31, v146
	v_lshl_add_u64 v[148:149], s[4:5], 0, v[148:149]
	v_lshl_add_u64 v[206:207], v[146:147], 1, v[148:149]
	v_add_co_u32_e32 v216, vcc, s67, v206
	s_lshl_b64 s[26:27], s[26:27], 2
	s_nop 0
	v_addc_co_u32_e32 v217, vcc, 0, v207, vcc
	v_add_co_u32_e32 v252, vcc, s17, v206
	s_add_u32 s26, s51, s26
	s_nop 0
	v_addc_co_u32_e32 v253, vcc, 0, v207, vcc
	v_add_co_u32_e32 v200, vcc, s74, v206
	s_addc_u32 s27, s52, s27
	s_nop 0
	v_addc_co_u32_e32 v201, vcc, 0, v207, vcc
	v_add_co_u32_e32 v198, vcc, s64, v206
	v_lshl_add_u64 v[134:135], v[146:147], 2, s[26:27]
	s_nop 0
	v_addc_co_u32_e32 v199, vcc, 0, v207, vcc
	v_add_co_u32_e32 v196, vcc, s31, v206
	s_mov_b32 s26, 0xb0000
	s_nop 0
	v_addc_co_u32_e32 v197, vcc, 0, v207, vcc
	v_add_co_u32_e32 v194, vcc, s65, v206
	global_load_dwordx4 v[138:141], v[134:135], off offset:16
	global_load_dwordx4 v[142:145], v[134:135], off
	global_load_dwordx4 v[130:133], v[134:135], off offset:528
	s_nop 0
	global_load_dwordx4 v[134:137], v[134:135], off offset:512
	v_addc_co_u32_e32 v195, vcc, 0, v207, vcc
	v_add_co_u32_e32 v192, vcc, s26, v206
	global_load_dwordx4 v[224:227], v[206:207], off
	global_load_dwordx4 v[228:231], v[206:207], off offset:256
	v_addc_co_u32_e32 v193, vcc, 0, v207, vcc
	global_load_dwordx4 v[232:235], v[216:217], off
	global_load_dwordx4 v[236:239], v[216:217], off offset:256
	global_load_dwordx4 v[240:243], v[252:253], off
	global_load_dwordx4 v[244:247], v[252:253], off offset:256
	global_load_dwordx4 v[248:251], v[200:201], off
	global_load_dwordx4 v[178:181], v[200:201], off offset:256
	global_load_dwordx4 v[174:177], v[198:199], off
	global_load_dwordx4 v[170:173], v[198:199], off offset:256
	global_load_dwordx4 v[166:169], v[196:197], off
	global_load_dwordx4 v[162:165], v[196:197], off offset:256
	global_load_dwordx4 v[158:161], v[194:195], off
	global_load_dwordx4 v[154:157], v[194:195], off offset:256
	global_load_dwordx4 v[150:153], v[192:193], off
	global_load_dwordx4 v[146:149], v[192:193], off offset:256
	s_waitcnt vmcnt(0)
	v_lshlrev_b32_e32 v223, 16, v224
	v_fmac_f32_e32 v223, v126, v142
	v_and_b32_e32 v126, 0xffff0000, v224
	v_fmac_f32_e32 v126, v127, v143
	v_lshlrev_b32_e32 v127, 16, v225
	v_fmac_f32_e32 v127, v128, v144
	v_and_b32_e32 v128, 0xffff0000, v225
	v_fmac_f32_e32 v128, v129, v145
	v_cvt_pk_bf16_f32 v126, v223, v126
	v_cvt_pk_bf16_f32 v127, v127, v128
	v_lshlrev_b32_e32 v128, 16, v226
	v_fmac_f32_e32 v128, v122, v138
	v_and_b32_e32 v122, 0xffff0000, v226
	v_fmac_f32_e32 v122, v123, v139
	v_cvt_pk_bf16_f32 v128, v128, v122
	v_lshlrev_b32_e32 v122, 16, v227
	v_fmac_f32_e32 v122, v124, v140
	v_and_b32_e32 v123, 0xffff0000, v227
	v_fmac_f32_e32 v123, v125, v141
	v_cvt_pk_bf16_f32 v129, v122, v123
	v_lshlrev_b32_e32 v122, 16, v228
	v_fmac_f32_e32 v122, v118, v134
	v_and_b32_e32 v118, 0xffff0000, v228
	v_fmac_f32_e32 v118, v119, v135
	v_lshlrev_b32_e32 v119, 16, v229
	v_fmac_f32_e32 v119, v120, v136
	v_and_b32_e32 v120, 0xffff0000, v229
	v_fmac_f32_e32 v120, v121, v137
	global_store_dwordx4 v[206:207], v[126:129], off sc1
	v_cvt_pk_bf16_f32 v118, v122, v118
	v_cvt_pk_bf16_f32 v119, v119, v120
	v_lshlrev_b32_e32 v120, 16, v230
	v_fmac_f32_e32 v120, v110, v130
	v_and_b32_e32 v110, 0xffff0000, v230
	v_fmac_f32_e32 v110, v111, v131
	v_cvt_pk_bf16_f32 v120, v120, v110
	v_lshlrev_b32_e32 v110, 16, v231
	v_and_b32_e32 v111, 0xffff0000, v231
	v_fmac_f32_e32 v110, v112, v132
	v_fmac_f32_e32 v111, v113, v133
	v_cvt_pk_bf16_f32 v121, v110, v111
	v_lshlrev_b32_e32 v110, 16, v232
	v_and_b32_e32 v111, 0xffff0000, v232
	v_fmac_f32_e32 v110, v114, v142
	v_fmac_f32_e32 v111, v115, v143
	global_store_dwordx4 v[206:207], v[118:121], off offset:256 sc1
	v_cvt_pk_bf16_f32 v110, v110, v111
	v_lshlrev_b32_e32 v111, 16, v233
	v_and_b32_e32 v112, 0xffff0000, v233
	v_fmac_f32_e32 v111, v116, v144
	v_fmac_f32_e32 v112, v117, v145
	v_cvt_pk_bf16_f32 v111, v111, v112
	v_lshlrev_b32_e32 v112, 16, v234
	v_fmac_f32_e32 v112, v106, v138
	v_and_b32_e32 v106, 0xffff0000, v234
	v_fmac_f32_e32 v106, v107, v139
	v_cvt_pk_bf16_f32 v112, v112, v106
	v_lshlrev_b32_e32 v106, 16, v235
	v_fmac_f32_e32 v106, v108, v140
	v_and_b32_e32 v107, 0xffff0000, v235
	v_fmac_f32_e32 v107, v109, v141
	v_cvt_pk_bf16_f32 v113, v106, v107
	v_lshlrev_b32_e32 v106, 16, v236
	v_fmac_f32_e32 v106, v102, v134
	v_and_b32_e32 v102, 0xffff0000, v236
	v_fmac_f32_e32 v102, v103, v135
	v_lshlrev_b32_e32 v103, 16, v237
	v_fmac_f32_e32 v103, v104, v136
	v_and_b32_e32 v104, 0xffff0000, v237
	v_fmac_f32_e32 v104, v105, v137
	global_store_dwordx4 v[216:217], v[110:113], off sc1
	v_cvt_pk_bf16_f32 v102, v106, v102
	v_cvt_pk_bf16_f32 v103, v103, v104
	v_lshlrev_b32_e32 v104, 16, v238
	v_fmac_f32_e32 v104, v94, v130
	v_and_b32_e32 v94, 0xffff0000, v238
	v_fmac_f32_e32 v94, v95, v131
	v_cvt_pk_bf16_f32 v104, v104, v94
	v_lshlrev_b32_e32 v94, 16, v239
	v_and_b32_e32 v95, 0xffff0000, v239
	v_fmac_f32_e32 v94, v96, v132
	v_fmac_f32_e32 v95, v97, v133
	v_cvt_pk_bf16_f32 v105, v94, v95
	v_lshlrev_b32_e32 v94, 16, v240
	v_and_b32_e32 v95, 0xffff0000, v240
	v_fmac_f32_e32 v94, v98, v142
	v_fmac_f32_e32 v95, v99, v143
	global_store_dwordx4 v[216:217], v[102:105], off offset:256 sc1
	v_cvt_pk_bf16_f32 v94, v94, v95
	v_lshlrev_b32_e32 v95, 16, v241
	v_and_b32_e32 v96, 0xffff0000, v241
	v_fmac_f32_e32 v95, v100, v144
	v_fmac_f32_e32 v96, v101, v145
	v_cvt_pk_bf16_f32 v95, v95, v96
	v_lshlrev_b32_e32 v96, 16, v242
	v_fmac_f32_e32 v96, v90, v138
	v_and_b32_e32 v90, 0xffff0000, v242
	v_fmac_f32_e32 v90, v91, v139
	v_cvt_pk_bf16_f32 v96, v96, v90
	v_lshlrev_b32_e32 v90, 16, v243
	v_fmac_f32_e32 v90, v92, v140
	v_and_b32_e32 v91, 0xffff0000, v243
	v_fmac_f32_e32 v91, v93, v141
	v_cvt_pk_bf16_f32 v97, v90, v91
	v_lshlrev_b32_e32 v90, 16, v244
	v_fmac_f32_e32 v90, v86, v134
	v_and_b32_e32 v86, 0xffff0000, v244
	v_fmac_f32_e32 v86, v87, v135
	v_lshlrev_b32_e32 v87, 16, v245
	v_fmac_f32_e32 v87, v88, v136
	v_and_b32_e32 v88, 0xffff0000, v245
	v_fmac_f32_e32 v88, v89, v137
	global_store_dwordx4 v[252:253], v[94:97], off sc1
	v_cvt_pk_bf16_f32 v86, v90, v86
	v_cvt_pk_bf16_f32 v87, v87, v88
	v_lshlrev_b32_e32 v88, 16, v246
	v_fmac_f32_e32 v88, v78, v130
	v_and_b32_e32 v78, 0xffff0000, v246
	v_fmac_f32_e32 v78, v79, v131
	v_cvt_pk_bf16_f32 v88, v88, v78
	v_lshlrev_b32_e32 v78, 16, v247
	v_and_b32_e32 v79, 0xffff0000, v247
	v_fmac_f32_e32 v78, v80, v132
	v_fmac_f32_e32 v79, v81, v133
	v_cvt_pk_bf16_f32 v89, v78, v79
	v_lshlrev_b32_e32 v78, 16, v248
	v_and_b32_e32 v79, 0xffff0000, v248
	v_fmac_f32_e32 v78, v82, v142
	v_fmac_f32_e32 v79, v83, v143
	global_store_dwordx4 v[252:253], v[86:89], off offset:256 sc1
	v_cvt_pk_bf16_f32 v78, v78, v79
	v_lshlrev_b32_e32 v79, 16, v249
	v_and_b32_e32 v80, 0xffff0000, v249
	v_fmac_f32_e32 v79, v84, v144
	v_fmac_f32_e32 v80, v85, v145
	v_cvt_pk_bf16_f32 v79, v79, v80
	v_lshlrev_b32_e32 v80, 16, v250
	v_fmac_f32_e32 v80, v74, v138
	v_and_b32_e32 v74, 0xffff0000, v250
	v_fmac_f32_e32 v74, v75, v139
	v_cvt_pk_bf16_f32 v80, v80, v74
	v_lshlrev_b32_e32 v74, 16, v251
	v_fmac_f32_e32 v74, v76, v140
	v_and_b32_e32 v75, 0xffff0000, v251
	v_fmac_f32_e32 v75, v77, v141
	v_cvt_pk_bf16_f32 v81, v74, v75
	v_lshlrev_b32_e32 v74, 16, v178
	v_fmac_f32_e32 v74, v70, v134
	v_and_b32_e32 v70, 0xffff0000, v178
	v_fmac_f32_e32 v70, v71, v135
	v_lshlrev_b32_e32 v71, 16, v179
	v_fmac_f32_e32 v71, v72, v136
	v_and_b32_e32 v72, 0xffff0000, v179
	v_fmac_f32_e32 v72, v73, v137
	global_store_dwordx4 v[200:201], v[78:81], off sc1
	v_cvt_pk_bf16_f32 v70, v74, v70
	v_cvt_pk_bf16_f32 v71, v71, v72
	v_lshlrev_b32_e32 v72, 16, v180
	v_fmac_f32_e32 v72, v66, v130
	v_and_b32_e32 v66, 0xffff0000, v180
	v_fmac_f32_e32 v66, v67, v131
	v_cvt_pk_bf16_f32 v72, v72, v66
	v_lshlrev_b32_e32 v66, 16, v181
	v_fmac_f32_e32 v66, v68, v132
	v_and_b32_e32 v67, 0xffff0000, v181
	v_fmac_f32_e32 v67, v69, v133
	v_cvt_pk_bf16_f32 v73, v66, v67
	v_lshlrev_b32_e32 v66, 16, v174
	v_fmac_f32_e32 v66, v62, v142
	v_and_b32_e32 v62, 0xffff0000, v174
	v_fmac_f32_e32 v62, v63, v143
	v_lshlrev_b32_e32 v63, 16, v175
	v_fmac_f32_e32 v63, v64, v144
	v_and_b32_e32 v64, 0xffff0000, v175
	v_fmac_f32_e32 v64, v65, v145
	global_store_dwordx4 v[200:201], v[70:73], off offset:256 sc1
	v_cvt_pk_bf16_f32 v62, v66, v62
	v_cvt_pk_bf16_f32 v63, v63, v64
	v_lshlrev_b32_e32 v64, 16, v176
	v_fmac_f32_e32 v64, v58, v138
	v_and_b32_e32 v58, 0xffff0000, v176
	v_fmac_f32_e32 v58, v59, v139
	v_cvt_pk_bf16_f32 v64, v64, v58
	v_lshlrev_b32_e32 v58, 16, v177
	v_fmac_f32_e32 v58, v60, v140
	v_and_b32_e32 v59, 0xffff0000, v177
	v_fmac_f32_e32 v59, v61, v141
	v_cvt_pk_bf16_f32 v65, v58, v59
	v_lshlrev_b32_e32 v58, 16, v170
	v_fmac_f32_e32 v58, v54, v134
	v_and_b32_e32 v54, 0xffff0000, v170
	v_fmac_f32_e32 v54, v55, v135
	v_lshlrev_b32_e32 v55, 16, v171
	v_fmac_f32_e32 v55, v56, v136
	v_and_b32_e32 v56, 0xffff0000, v171
	v_fmac_f32_e32 v56, v57, v137
	global_store_dwordx4 v[198:199], v[62:65], off sc1
	v_cvt_pk_bf16_f32 v54, v58, v54
	v_cvt_pk_bf16_f32 v55, v55, v56
	v_lshlrev_b32_e32 v56, 16, v172
	v_fmac_f32_e32 v56, v46, v130
	v_and_b32_e32 v46, 0xffff0000, v172
	v_fmac_f32_e32 v46, v47, v131
	v_cvt_pk_bf16_f32 v56, v56, v46
	v_lshlrev_b32_e32 v46, 16, v173
	v_and_b32_e32 v47, 0xffff0000, v173
	v_fmac_f32_e32 v46, v48, v132
	v_fmac_f32_e32 v47, v49, v133
	v_cvt_pk_bf16_f32 v57, v46, v47
	v_lshlrev_b32_e32 v46, 16, v166
	v_and_b32_e32 v47, 0xffff0000, v166
	v_fmac_f32_e32 v46, v50, v142
	v_fmac_f32_e32 v47, v51, v143
	global_store_dwordx4 v[198:199], v[54:57], off offset:256 sc1
	v_cvt_pk_bf16_f32 v46, v46, v47
	v_lshlrev_b32_e32 v47, 16, v167
	v_and_b32_e32 v48, 0xffff0000, v167
	v_fmac_f32_e32 v47, v52, v144
	v_fmac_f32_e32 v48, v53, v145
	v_cvt_pk_bf16_f32 v47, v47, v48
	v_lshlrev_b32_e32 v48, 16, v168
	v_fmac_f32_e32 v48, v42, v138
	v_and_b32_e32 v42, 0xffff0000, v168
	v_fmac_f32_e32 v42, v43, v139
	v_cvt_pk_bf16_f32 v48, v48, v42
	v_lshlrev_b32_e32 v42, 16, v169
	v_fmac_f32_e32 v42, v44, v140
	v_and_b32_e32 v43, 0xffff0000, v169
	v_fmac_f32_e32 v43, v45, v141
	v_cvt_pk_bf16_f32 v49, v42, v43
	v_lshlrev_b32_e32 v42, 16, v162
	v_fmac_f32_e32 v42, v38, v134
	v_and_b32_e32 v38, 0xffff0000, v162
	v_fmac_f32_e32 v38, v39, v135
	v_lshlrev_b32_e32 v39, 16, v163
	v_fmac_f32_e32 v39, v40, v136
	v_and_b32_e32 v40, 0xffff0000, v163
	v_fmac_f32_e32 v40, v41, v137
	global_store_dwordx4 v[196:197], v[46:49], off sc1
	v_cvt_pk_bf16_f32 v38, v42, v38
	v_cvt_pk_bf16_f32 v39, v39, v40
	v_lshlrev_b32_e32 v40, 16, v164
	v_fmac_f32_e32 v40, v30, v130
	v_and_b32_e32 v30, 0xffff0000, v164
	v_fmac_f32_e32 v30, v31, v131
	v_cvt_pk_bf16_f32 v40, v40, v30
	v_lshlrev_b32_e32 v30, 16, v165
	v_and_b32_e32 v31, 0xffff0000, v165
	v_fmac_f32_e32 v30, v32, v132
	v_fmac_f32_e32 v31, v33, v133
	v_cvt_pk_bf16_f32 v41, v30, v31
	v_lshlrev_b32_e32 v30, 16, v158
	v_and_b32_e32 v31, 0xffff0000, v158
	v_fmac_f32_e32 v30, v34, v142
	v_fmac_f32_e32 v31, v35, v143
	global_store_dwordx4 v[196:197], v[38:41], off offset:256 sc1
	v_cvt_pk_bf16_f32 v30, v30, v31
	v_lshlrev_b32_e32 v31, 16, v159
	v_and_b32_e32 v32, 0xffff0000, v159
	v_fmac_f32_e32 v31, v36, v144
	v_fmac_f32_e32 v32, v37, v145
	v_cvt_pk_bf16_f32 v31, v31, v32
	v_lshlrev_b32_e32 v32, 16, v160
	v_fmac_f32_e32 v32, v26, v138
	v_and_b32_e32 v26, 0xffff0000, v160
	v_fmac_f32_e32 v26, v27, v139
	v_cvt_pk_bf16_f32 v32, v32, v26
	v_lshlrev_b32_e32 v26, 16, v161
	v_fmac_f32_e32 v26, v28, v140
	v_and_b32_e32 v27, 0xffff0000, v161
	v_fmac_f32_e32 v27, v29, v141
	v_cvt_pk_bf16_f32 v33, v26, v27
	v_lshlrev_b32_e32 v26, 16, v154
	v_fmac_f32_e32 v26, v22, v134
	v_and_b32_e32 v22, 0xffff0000, v154
	v_fmac_f32_e32 v22, v23, v135
	v_lshlrev_b32_e32 v23, 16, v155
	v_fmac_f32_e32 v23, v24, v136
	v_and_b32_e32 v24, 0xffff0000, v155
	v_fmac_f32_e32 v24, v25, v137
	global_store_dwordx4 v[194:195], v[30:33], off sc1
	v_cvt_pk_bf16_f32 v22, v26, v22
	v_cvt_pk_bf16_f32 v23, v23, v24
	v_lshlrev_b32_e32 v24, 16, v156
	v_fmac_f32_e32 v24, v12, v130
	v_and_b32_e32 v12, 0xffff0000, v156
	v_fmac_f32_e32 v12, v13, v131
	v_cvt_pk_bf16_f32 v24, v24, v12
	v_lshlrev_b32_e32 v12, 16, v157
	v_and_b32_e32 v13, 0xffff0000, v157
	v_fmac_f32_e32 v12, v14, v132
	v_fmac_f32_e32 v13, v15, v133
	v_cvt_pk_bf16_f32 v25, v12, v13
	v_lshlrev_b32_e32 v12, 16, v150
	v_and_b32_e32 v13, 0xffff0000, v150
	v_fmac_f32_e32 v12, v18, v142
	v_fmac_f32_e32 v13, v19, v143
	global_store_dwordx4 v[194:195], v[22:25], off offset:256 sc1
	v_cvt_pk_bf16_f32 v12, v12, v13
	v_lshlrev_b32_e32 v13, 16, v151
	v_and_b32_e32 v14, 0xffff0000, v151
	v_fmac_f32_e32 v13, v20, v144
	v_fmac_f32_e32 v14, v21, v145
	v_cvt_pk_bf16_f32 v13, v13, v14
	v_lshlrev_b32_e32 v14, 16, v152
	v_fmac_f32_e32 v14, v8, v138
	v_and_b32_e32 v8, 0xffff0000, v152
	v_fmac_f32_e32 v8, v9, v139
	v_cvt_pk_bf16_f32 v14, v14, v8
	v_lshlrev_b32_e32 v8, 16, v153
	v_fmac_f32_e32 v8, v10, v140
	v_and_b32_e32 v9, 0xffff0000, v153
	v_fmac_f32_e32 v9, v11, v141
	v_cvt_pk_bf16_f32 v15, v8, v9
	v_lshlrev_b32_e32 v8, 16, v146
	v_fmac_f32_e32 v8, v4, v134
	v_and_b32_e32 v4, 0xffff0000, v146
	v_fmac_f32_e32 v4, v5, v135
	v_lshlrev_b32_e32 v5, 16, v147
	v_fmac_f32_e32 v5, v6, v136
	v_and_b32_e32 v6, 0xffff0000, v147
	v_fmac_f32_e32 v6, v7, v137
	global_store_dwordx4 v[192:193], v[12:15], off sc1
	v_cvt_pk_bf16_f32 v4, v8, v4
	v_cvt_pk_bf16_f32 v5, v5, v6
	v_lshlrev_b32_e32 v6, 16, v148
	v_fmac_f32_e32 v6, v0, v130
	v_and_b32_e32 v0, 0xffff0000, v148
	v_fmac_f32_e32 v0, v1, v131
	v_cvt_pk_bf16_f32 v6, v6, v0
	v_lshlrev_b32_e32 v0, 16, v149
	v_and_b32_e32 v1, 0xffff0000, v149
	s_and_b64 vcc, exec, s[38:39]
	s_mov_b64 s[26:27], -1
	v_fmac_f32_e32 v0, v2, v132
	v_fmac_f32_e32 v1, v3, v133
	v_cvt_pk_bf16_f32 v7, v0, v1
	global_store_dwordx4 v[192:193], v[4:7], off offset:256 sc1
	s_cbranch_vccnz .LBB0_984
	s_andn2_b64 vcc, exec, s[0:1]
	s_cbranch_vccnz .LBB0_983
	s_barrier
	s_branch .LBB0_983
